# GEMM K-loops: MFMA/LDS interleave - the 4 B1-fragment ds_read_b128 of phases 2 and 6 are issued inside the preceding phase's MFMA block
# baseline (speedup 1.0000x reference)
.LBB0_197:
	ds_read_b128 v[144:147], v151
	ds_read_b128 v[154:157], v151 offset:1024
	ds_read_b128 v[158:161], v151 offset:2048
	ds_read_b128 v[162:165], v151 offset:3072
	s_add_u32 s18, s16, 0xfff80080
	s_addc_u32 s19, s17, -1
	s_cmp_eq_u32 s78, 28
	s_cselect_b32 s21, s5, s19
	s_cselect_b32 s20, s9, s18
	s_cselect_b32 s19, s7, s77
	s_cselect_b32 s18, s15, s76
	s_add_i32 m0, s24, 0xc000
	ds_read_b128 v[166:169], v152
	ds_read_b128 v[170:173], v152 offset:1024
	ds_read_b128 v[174:177], v152 offset:2048
	ds_read_b128 v[178:181], v152 offset:3072
	ds_read_b128 v[182:185], v152 offset:4096
	ds_read_b128 v[186:189], v152 offset:5120
	ds_read_b128 v[190:193], v152 offset:6144
	ds_read_b128 v[194:197], v152 offset:7168
	global_load_lds_dwordx4 v136, s[16:17]
	s_add_i32 m0, s24, 0xe000
	s_nop 0
	global_load_lds_dwordx4 v138, s[16:17]
	s_waitcnt lgkmcnt(8)
	s_barrier
	s_waitcnt lgkmcnt(0)
	v_mfma_f32_16x16x32_f16 v[124:127], v[144:147], v[166:169], v[124:127]
	v_mfma_f32_16x16x32_f16 v[120:123], v[158:161], v[166:169], v[120:123]
	ds_read_b128 v[198:201], v153
	v_mfma_f32_16x16x32_f16 v[108:111], v[144:147], v[174:177], v[108:111]
	v_mfma_f32_16x16x32_f16 v[104:107], v[158:161], v[174:177], v[104:107]
	v_mfma_f32_16x16x32_f16 v[92:95], v[144:147], v[182:185], v[92:95]
	ds_read_b128 v[202:205], v153 offset:1024
	v_mfma_f32_16x16x32_f16 v[88:91], v[158:161], v[182:185], v[88:91]
	v_mfma_f32_16x16x32_f16 v[76:79], v[144:147], v[190:193], v[76:79]
	v_mfma_f32_16x16x32_f16 v[72:75], v[158:161], v[190:193], v[72:75]
	ds_read_b128 v[206:209], v153 offset:2048
	v_mfma_f32_16x16x32_f16 v[124:127], v[154:157], v[170:173], v[124:127]
	v_mfma_f32_16x16x32_f16 v[120:123], v[162:165], v[170:173], v[120:123]
	v_mfma_f32_16x16x32_f16 v[108:111], v[154:157], v[178:181], v[108:111]
	ds_read_b128 v[210:213], v153 offset:3072
	v_mfma_f32_16x16x32_f16 v[104:107], v[162:165], v[178:181], v[104:107]
	v_mfma_f32_16x16x32_f16 v[92:95], v[154:157], v[186:189], v[92:95]
	v_mfma_f32_16x16x32_f16 v[88:91], v[162:165], v[186:189], v[88:91]
	v_mfma_f32_16x16x32_f16 v[76:79], v[154:157], v[194:197], v[76:79]
	v_mfma_f32_16x16x32_f16 v[72:75], v[162:165], v[194:197], v[72:75]
	s_barrier
	s_add_i32 s79, s68, s23
	s_add_u32 s72, s18, s0
	s_addc_u32 s73, s19, s1
	s_mov_b32 m0, s79
	s_nop 0
	global_load_lds_dwordx4 v130, s[18:19]
	s_add_i32 m0, s79, 0x2000
	s_nop 0
	global_load_lds_dwordx4 v134, s[18:19]
	s_barrier
	s_waitcnt lgkmcnt(0)
	v_mfma_f32_16x16x32_f16 v[116:119], v[198:201], v[166:169], v[116:119]
	v_mfma_f32_16x16x32_f16 v[112:115], v[206:209], v[166:169], v[112:115]
	v_mfma_f32_16x16x32_f16 v[100:103], v[198:201], v[174:177], v[100:103]
	v_mfma_f32_16x16x32_f16 v[96:99], v[206:209], v[174:177], v[96:99]
	v_mfma_f32_16x16x32_f16 v[84:87], v[198:201], v[182:185], v[84:87]
	v_mfma_f32_16x16x32_f16 v[80:83], v[206:209], v[182:185], v[80:83]
	v_mfma_f32_16x16x32_f16 v[68:71], v[198:201], v[190:193], v[68:71]
	v_mfma_f32_16x16x32_f16 v[64:67], v[206:209], v[190:193], v[64:67]
	v_mfma_f32_16x16x32_f16 v[116:119], v[202:205], v[170:173], v[116:119]
	v_mfma_f32_16x16x32_f16 v[112:115], v[210:213], v[170:173], v[112:115]
	v_mfma_f32_16x16x32_f16 v[100:103], v[202:205], v[178:181], v[100:103]
	v_mfma_f32_16x16x32_f16 v[96:99], v[210:213], v[178:181], v[96:99]
	v_mfma_f32_16x16x32_f16 v[84:87], v[202:205], v[186:189], v[84:87]
	v_mfma_f32_16x16x32_f16 v[80:83], v[210:213], v[186:189], v[80:83]
	v_mfma_f32_16x16x32_f16 v[68:71], v[202:205], v[194:197], v[68:71]
	v_mfma_f32_16x16x32_f16 v[64:67], v[210:213], v[194:197], v[64:67]
	s_barrier
	s_mov_b32 m0, s24
	s_add_u32 s74, s20, s0
	s_addc_u32 s75, s21, s1
	ds_read_b128 v[166:169], v152 offset:16384
	ds_read_b128 v[170:173], v152 offset:17408
	ds_read_b128 v[174:177], v152 offset:18432
	ds_read_b128 v[178:181], v152 offset:19456
	ds_read_b128 v[182:185], v152 offset:20480
	ds_read_b128 v[186:189], v152 offset:21504
	ds_read_b128 v[190:193], v152 offset:22528
	ds_read_b128 v[194:197], v152 offset:23552
	global_load_lds_dwordx4 v128, s[20:21]
	s_mov_b32 m0, s25
	s_nop 0
	global_load_lds_dwordx4 v132, s[20:21]
	s_barrier
	s_waitcnt lgkmcnt(0)
	v_mfma_f32_16x16x32_f16 v[60:63], v[144:147], v[166:169], v[60:63]
	v_mfma_f32_16x16x32_f16 v[56:59], v[158:161], v[166:169], v[56:59]
	v_mfma_f32_16x16x32_f16 v[44:47], v[144:147], v[174:177], v[44:47]
	v_mfma_f32_16x16x32_f16 v[40:43], v[158:161], v[174:177], v[40:43]
	v_mfma_f32_16x16x32_f16 v[28:31], v[144:147], v[182:185], v[28:31]
	v_mfma_f32_16x16x32_f16 v[24:27], v[158:161], v[182:185], v[24:27]
	v_mfma_f32_16x16x32_f16 v[12:15], v[144:147], v[190:193], v[12:15]
	v_mfma_f32_16x16x32_f16 v[8:11], v[158:161], v[190:193], v[8:11]
	v_mfma_f32_16x16x32_f16 v[60:63], v[154:157], v[170:173], v[60:63]
	v_mfma_f32_16x16x32_f16 v[56:59], v[162:165], v[170:173], v[56:59]
	v_mfma_f32_16x16x32_f16 v[44:47], v[154:157], v[178:181], v[44:47]
	v_mfma_f32_16x16x32_f16 v[40:43], v[162:165], v[178:181], v[40:43]
	v_mfma_f32_16x16x32_f16 v[28:31], v[154:157], v[186:189], v[28:31]
	v_mfma_f32_16x16x32_f16 v[24:27], v[162:165], v[186:189], v[24:27]
	v_mfma_f32_16x16x32_f16 v[12:15], v[154:157], v[194:197], v[12:15]
	v_mfma_f32_16x16x32_f16 v[8:11], v[162:165], v[194:197], v[8:11]
	s_barrier
	s_add_u32 s80, s18, 0x80000
	s_addc_u32 s81, s19, 0
	s_add_i32 s79, s69, s23
	s_mov_b32 m0, s79
	s_nop 0
	global_load_lds_dwordx4 v130, s[80:81]
	s_add_i32 m0, s79, 0x2000
	s_nop 0
	global_load_lds_dwordx4 v134, s[80:81]
	s_waitcnt vmcnt(6)
	s_barrier
	v_mfma_f32_16x16x32_f16 v[52:55], v[198:201], v[166:169], v[52:55]
	v_mfma_f32_16x16x32_f16 v[48:51], v[206:209], v[166:169], v[48:51]
	v_mfma_f32_16x16x32_f16 v[36:39], v[198:201], v[174:177], v[36:39]
	v_mfma_f32_16x16x32_f16 v[32:35], v[206:209], v[174:177], v[32:35]
	v_mfma_f32_16x16x32_f16 v[20:23], v[198:201], v[182:185], v[20:23]
	v_mfma_f32_16x16x32_f16 v[16:19], v[206:209], v[182:185], v[16:19]
	v_mfma_f32_16x16x32_f16 v[4:7], v[198:201], v[190:193], v[4:7]
	v_mfma_f32_16x16x32_f16 v[0:3], v[206:209], v[190:193], v[0:3]
	v_mfma_f32_16x16x32_f16 v[52:55], v[202:205], v[170:173], v[52:55]
	v_mfma_f32_16x16x32_f16 v[48:51], v[210:213], v[170:173], v[48:51]
	v_mfma_f32_16x16x32_f16 v[36:39], v[202:205], v[178:181], v[36:39]
	v_mfma_f32_16x16x32_f16 v[32:35], v[210:213], v[178:181], v[32:35]
	v_mfma_f32_16x16x32_f16 v[20:23], v[202:205], v[186:189], v[20:23]
	v_mfma_f32_16x16x32_f16 v[16:19], v[210:213], v[186:189], v[16:19]
	v_mfma_f32_16x16x32_f16 v[4:7], v[202:205], v[194:197], v[4:7]
	v_mfma_f32_16x16x32_f16 v[0:3], v[210:213], v[194:197], v[0:3]
	s_barrier
	s_add_i32 s79, 0, 0x18000
	v_add_u32_e32 v162, s79, v149
	ds_read_b128 v[144:147], v162
	ds_read_b128 v[154:157], v162 offset:1024
	ds_read_b128 v[158:161], v162 offset:2048
	ds_read_b128 v[162:165], v162 offset:3072
	s_add_u32 s20, s20, 0x80000
	s_addc_u32 s21, s21, 0
	s_mov_b32 m0, s26
	ds_read_b128 v[166:169], v152 offset:32768
	ds_read_b128 v[170:173], v152 offset:33792
	ds_read_b128 v[174:177], v152 offset:34816
	ds_read_b128 v[178:181], v152 offset:35840
	ds_read_b128 v[182:185], v152 offset:36864
	ds_read_b128 v[186:189], v152 offset:37888
	ds_read_b128 v[190:193], v152 offset:38912
	ds_read_b128 v[194:197], v152 offset:39936
	global_load_lds_dwordx4 v128, s[20:21]
	s_mov_b32 m0, s27
	s_nop 0
	global_load_lds_dwordx4 v132, s[20:21]
	s_waitcnt lgkmcnt(8)
	s_barrier
	s_waitcnt lgkmcnt(0)
	v_mfma_f32_16x16x32_f16 v[124:127], v[144:147], v[166:169], v[124:127]
	v_mfma_f32_16x16x32_f16 v[120:123], v[158:161], v[166:169], v[120:123]
	v_add_u32_e32 v210, 0x1c000, v149
	ds_read_b128 v[198:201], v210
	v_mfma_f32_16x16x32_f16 v[108:111], v[144:147], v[174:177], v[108:111]
	v_mfma_f32_16x16x32_f16 v[104:107], v[158:161], v[174:177], v[104:107]
	v_mfma_f32_16x16x32_f16 v[92:95], v[144:147], v[182:185], v[92:95]
	ds_read_b128 v[202:205], v210 offset:1024
	v_mfma_f32_16x16x32_f16 v[88:91], v[158:161], v[182:185], v[88:91]
	v_mfma_f32_16x16x32_f16 v[76:79], v[144:147], v[190:193], v[76:79]
	v_mfma_f32_16x16x32_f16 v[72:75], v[158:161], v[190:193], v[72:75]
	ds_read_b128 v[206:209], v210 offset:2048
	v_mfma_f32_16x16x32_f16 v[124:127], v[154:157], v[170:173], v[124:127]
	v_mfma_f32_16x16x32_f16 v[120:123], v[162:165], v[170:173], v[120:123]
	v_mfma_f32_16x16x32_f16 v[108:111], v[154:157], v[178:181], v[108:111]
	ds_read_b128 v[210:213], v210 offset:3072
	v_mfma_f32_16x16x32_f16 v[104:107], v[162:165], v[178:181], v[104:107]
	v_mfma_f32_16x16x32_f16 v[92:95], v[154:157], v[186:189], v[92:95]
	v_mfma_f32_16x16x32_f16 v[88:91], v[162:165], v[186:189], v[88:91]
	v_mfma_f32_16x16x32_f16 v[76:79], v[154:157], v[194:197], v[76:79]
	v_mfma_f32_16x16x32_f16 v[72:75], v[162:165], v[194:197], v[72:75]
	s_barrier
	s_add_i32 s20, 0, 0x1c000
	s_add_i32 s21, s79, s23
	s_mov_b32 m0, s21
	s_nop 0
	global_load_lds_dwordx4 v130, s[72:73]
	s_add_i32 m0, s21, 0x2000
	s_nop 0
	global_load_lds_dwordx4 v134, s[72:73]
	s_barrier
	s_waitcnt lgkmcnt(0)
	v_mfma_f32_16x16x32_f16 v[116:119], v[198:201], v[166:169], v[116:119]
	v_mfma_f32_16x16x32_f16 v[112:115], v[206:209], v[166:169], v[112:115]
	v_mfma_f32_16x16x32_f16 v[100:103], v[198:201], v[174:177], v[100:103]
	v_mfma_f32_16x16x32_f16 v[96:99], v[206:209], v[174:177], v[96:99]
	v_mfma_f32_16x16x32_f16 v[84:87], v[198:201], v[182:185], v[84:87]
	v_mfma_f32_16x16x32_f16 v[80:83], v[206:209], v[182:185], v[80:83]
	v_mfma_f32_16x16x32_f16 v[68:71], v[198:201], v[190:193], v[68:71]
	v_mfma_f32_16x16x32_f16 v[64:67], v[206:209], v[190:193], v[64:67]
	v_mfma_f32_16x16x32_f16 v[116:119], v[202:205], v[170:173], v[116:119]
	v_mfma_f32_16x16x32_f16 v[112:115], v[210:213], v[170:173], v[112:115]
	v_mfma_f32_16x16x32_f16 v[100:103], v[202:205], v[178:181], v[100:103]
	v_mfma_f32_16x16x32_f16 v[96:99], v[210:213], v[178:181], v[96:99]
	v_mfma_f32_16x16x32_f16 v[84:87], v[202:205], v[186:189], v[84:87]
	v_mfma_f32_16x16x32_f16 v[80:83], v[210:213], v[186:189], v[80:83]
	v_mfma_f32_16x16x32_f16 v[68:71], v[202:205], v[194:197], v[68:71]
	v_mfma_f32_16x16x32_f16 v[64:67], v[210:213], v[194:197], v[64:67]
	s_barrier
	s_mov_b32 m0, s29
	ds_read_b128 v[166:169], v152 offset:49152
	ds_read_b128 v[170:173], v152 offset:50176
	ds_read_b128 v[174:177], v152 offset:51200
	ds_read_b128 v[178:181], v152 offset:52224
	ds_read_b128 v[182:185], v152 offset:53248
	ds_read_b128 v[186:189], v152 offset:54272
	ds_read_b128 v[190:193], v152 offset:55296
	ds_read_b128 v[194:197], v152 offset:56320
	global_load_lds_dwordx4 v128, s[74:75]
	s_mov_b32 m0, s30
	s_nop 0
	global_load_lds_dwordx4 v132, s[74:75]
	s_barrier
	s_waitcnt lgkmcnt(0)
	v_mfma_f32_16x16x32_f16 v[60:63], v[144:147], v[166:169], v[60:63]
	v_mfma_f32_16x16x32_f16 v[56:59], v[158:161], v[166:169], v[56:59]
	v_mfma_f32_16x16x32_f16 v[44:47], v[144:147], v[174:177], v[44:47]
	v_mfma_f32_16x16x32_f16 v[40:43], v[158:161], v[174:177], v[40:43]
	v_mfma_f32_16x16x32_f16 v[28:31], v[144:147], v[182:185], v[28:31]
	v_mfma_f32_16x16x32_f16 v[24:27], v[158:161], v[182:185], v[24:27]
	v_mfma_f32_16x16x32_f16 v[12:15], v[144:147], v[190:193], v[12:15]
	v_mfma_f32_16x16x32_f16 v[8:11], v[158:161], v[190:193], v[8:11]
	v_mfma_f32_16x16x32_f16 v[60:63], v[154:157], v[170:173], v[60:63]
	v_mfma_f32_16x16x32_f16 v[56:59], v[162:165], v[170:173], v[56:59]
	v_mfma_f32_16x16x32_f16 v[44:47], v[154:157], v[178:181], v[44:47]
	v_mfma_f32_16x16x32_f16 v[40:43], v[162:165], v[178:181], v[40:43]
	v_mfma_f32_16x16x32_f16 v[28:31], v[154:157], v[186:189], v[28:31]
	v_mfma_f32_16x16x32_f16 v[24:27], v[162:165], v[186:189], v[24:27]
	v_mfma_f32_16x16x32_f16 v[12:15], v[154:157], v[194:197], v[12:15]
	v_mfma_f32_16x16x32_f16 v[8:11], v[162:165], v[194:197], v[8:11]
	s_barrier
	s_add_u32 s18, s18, 0x80080
	s_addc_u32 s19, s19, 0
	s_add_i32 s20, s20, s23
	s_mov_b32 m0, s20
	s_nop 0
	global_load_lds_dwordx4 v130, s[18:19]
	s_add_i32 m0, s20, 0x2000
	s_nop 0
	global_load_lds_dwordx4 v134, s[18:19]
	s_waitcnt vmcnt(6)
	s_barrier
	v_mfma_f32_16x16x32_f16 v[52:55], v[198:201], v[166:169], v[52:55]
	v_mfma_f32_16x16x32_f16 v[48:51], v[206:209], v[166:169], v[48:51]
	v_mfma_f32_16x16x32_f16 v[36:39], v[198:201], v[174:177], v[36:39]
	v_mfma_f32_16x16x32_f16 v[32:35], v[206:209], v[174:177], v[32:35]
	v_mfma_f32_16x16x32_f16 v[20:23], v[198:201], v[182:185], v[20:23]
	v_mfma_f32_16x16x32_f16 v[16:19], v[206:209], v[182:185], v[16:19]
	v_mfma_f32_16x16x32_f16 v[4:7], v[198:201], v[190:193], v[4:7]
	v_mfma_f32_16x16x32_f16 v[0:3], v[206:209], v[190:193], v[0:3]
	v_mfma_f32_16x16x32_f16 v[52:55], v[202:205], v[170:173], v[52:55]
	v_mfma_f32_16x16x32_f16 v[48:51], v[210:213], v[170:173], v[48:51]
	v_mfma_f32_16x16x32_f16 v[36:39], v[202:205], v[178:181], v[36:39]
	v_mfma_f32_16x16x32_f16 v[32:35], v[210:213], v[178:181], v[32:35]
	v_mfma_f32_16x16x32_f16 v[20:23], v[202:205], v[186:189], v[20:23]
	v_mfma_f32_16x16x32_f16 v[16:19], v[210:213], v[186:189], v[16:19]
	v_mfma_f32_16x16x32_f16 v[4:7], v[202:205], v[194:197], v[4:7]
	v_mfma_f32_16x16x32_f16 v[0:3], v[210:213], v[194:197], v[0:3]
	s_barrier
	s_add_i32 s78, s78, 2
	s_add_u32 s16, s16, 0x100
	s_addc_u32 s17, s17, 0
	s_add_u32 s76, s76, 0x100
	s_addc_u32 s77, s77, 0
	s_cmp_gt_u32 s78, 29
	s_cbranch_scc0 .LBB0_197
	s_setprio 0
	v_readlane_b32 s52, v254, 21
	v_readlane_b32 s54, v254, 23
	v_readlane_b32 s55, v254, 24
	v_lshl_add_u32 v154, s14, 8, v148
	v_lshl_or_b32 v144, s4, 8, v150
	v_mov_b64_e32 v[146:147], s[54:55]
	v_mad_i64_i32 v[146:147], s[4:5], v154, s70, v[146:147]
	v_cmp_gt_i32_e32 vcc, s71, v144
	v_ashrrev_i32_e32 v145, 31, v144
	v_readlane_b32 s53, v254, 22
	v_readlane_b32 s56, v254, 25
	v_readlane_b32 s57, v254, 26
	v_readlane_b32 s58, v254, 27
	v_readlane_b32 s59, v254, 28
	v_readlane_b32 s60, v254, 29
	v_readlane_b32 s61, v254, 30
	v_readlane_b32 s62, v254, 31
	v_readlane_b32 s63, v254, 32
	v_readlane_b32 s64, v254, 33
	v_readlane_b32 s65, v254, 34
	v_readlane_b32 s66, v254, 35
	v_readlane_b32 s67, v254, 36
	s_and_saveexec_b64 s[4:5], vcc
	s_cbranch_execz .LBB0_200
	v_cvt_pk_f16_f32 v123, v122, v123
	v_cvt_pk_f16_f32 v122, v120, v121
	v_cvt_pk_f16_f32 v121, v126, v127
	v_cvt_pk_f16_f32 v120, v124, v125
	v_lshl_add_u64 v[124:125], v[144:145], 1, v[146:147]
	global_store_dwordx4 v[124:125], v[120:123], off

.LBB0_647:
	ds_read_b128 v[80:83], v243
	ds_read_b128 v[88:91], v243 offset:1024
	ds_read_b128 v[96:99], v243 offset:2048
	ds_read_b128 v[100:103], v243 offset:3072
	s_add_u32 s18, s16, 0xfff80080
	s_addc_u32 s19, s17, -1
	s_cmp_eq_u32 s80, 28
	s_cselect_b32 s21, s9, s19
	s_cselect_b32 s20, s31, s18
	s_cselect_b32 s19, s7, s79
	s_cselect_b32 s18, s77, s78
	s_add_i32 m0, s15, 0xc000
	ds_read_b128 v[120:123], v244
	ds_read_b128 v[132:135], v244 offset:1024
	ds_read_b128 v[136:139], v244 offset:2048
	ds_read_b128 v[148:151], v244 offset:3072
	ds_read_b128 v[152:155], v244 offset:4096
	ds_read_b128 v[156:159], v244 offset:5120
	ds_read_b128 v[160:163], v244 offset:6144
	ds_read_b128 v[172:175], v244 offset:7168
	global_load_lds_dwordx4 v212, s[16:17]
	s_add_i32 m0, s15, 0xe000
	s_nop 0
	global_load_lds_dwordx4 v214, s[16:17]
	s_waitcnt lgkmcnt(8)
	s_barrier
	s_waitcnt lgkmcnt(0)
	v_mfma_f32_16x16x32_f16 v[168:171], v[80:83], v[120:123], v[168:171]
	v_mfma_f32_16x16x32_f16 v[164:167], v[96:99], v[120:123], v[164:167]
	ds_read_b128 v[176:179], v245
	v_mfma_f32_16x16x32_f16 v[128:131], v[80:83], v[136:139], v[128:131]
	v_mfma_f32_16x16x32_f16 v[124:127], v[96:99], v[136:139], v[124:127]
	v_mfma_f32_16x16x32_f16 v[108:111], v[80:83], v[152:155], v[108:111]
	ds_read_b128 v[180:183], v245 offset:1024
	v_mfma_f32_16x16x32_f16 v[104:107], v[96:99], v[152:155], v[104:107]
	v_mfma_f32_16x16x32_f16 v[76:79], v[80:83], v[160:163], v[76:79]
	v_mfma_f32_16x16x32_f16 v[72:75], v[96:99], v[160:163], v[72:75]
	ds_read_b128 v[184:187], v245 offset:2048
	v_mfma_f32_16x16x32_f16 v[168:171], v[88:91], v[132:135], v[168:171]
	v_mfma_f32_16x16x32_f16 v[164:167], v[100:103], v[132:135], v[164:167]
	v_mfma_f32_16x16x32_f16 v[128:131], v[88:91], v[148:151], v[128:131]
	ds_read_b128 v[188:191], v245 offset:3072
	v_mfma_f32_16x16x32_f16 v[124:127], v[100:103], v[148:151], v[124:127]
	v_mfma_f32_16x16x32_f16 v[108:111], v[88:91], v[156:159], v[108:111]
	v_mfma_f32_16x16x32_f16 v[104:107], v[100:103], v[156:159], v[104:107]
	v_mfma_f32_16x16x32_f16 v[76:79], v[88:91], v[172:175], v[76:79]
	v_mfma_f32_16x16x32_f16 v[72:75], v[100:103], v[172:175], v[72:75]
	s_barrier
	s_add_i32 s81, s71, s24
	s_add_u32 s72, s18, s4
	s_addc_u32 s73, s19, s5
	s_mov_b32 m0, s81
	s_nop 0
	global_load_lds_dwordx4 v206, s[18:19]
	s_add_i32 m0, s81, 0x2000
	s_nop 0
	global_load_lds_dwordx4 v210, s[18:19]
	s_barrier
	s_waitcnt lgkmcnt(0)
	v_mfma_f32_16x16x32_f16 v[144:147], v[176:179], v[120:123], v[144:147]
	v_mfma_f32_16x16x32_f16 v[116:119], v[176:179], v[136:139], v[116:119]
	v_mfma_f32_16x16x32_f16 v[112:115], v[184:187], v[136:139], v[112:115]
	v_mfma_f32_16x16x32_f16 v[92:95], v[176:179], v[152:155], v[92:95]
	v_mfma_f32_16x16x32_f16 v[84:87], v[184:187], v[152:155], v[84:87]
	v_mfma_f32_16x16x32_f16 v[68:71], v[176:179], v[160:163], v[68:71]
	v_mfma_f32_16x16x32_f16 v[64:67], v[184:187], v[160:163], v[64:67]
	v_mfma_f32_16x16x32_f16 v[144:147], v[180:183], v[132:135], v[144:147]
	v_mfma_f32_16x16x32_f16 v[120:123], v[184:187], v[120:123], v[140:143]
	v_mfma_f32_16x16x32_f16 v[116:119], v[180:183], v[148:151], v[116:119]
	v_mfma_f32_16x16x32_f16 v[112:115], v[188:191], v[148:151], v[112:115]
	v_mfma_f32_16x16x32_f16 v[92:95], v[180:183], v[156:159], v[92:95]
	v_mfma_f32_16x16x32_f16 v[84:87], v[188:191], v[156:159], v[84:87]
	v_mfma_f32_16x16x32_f16 v[68:71], v[180:183], v[172:175], v[68:71]
	v_mfma_f32_16x16x32_f16 v[64:67], v[188:191], v[172:175], v[64:67]
	v_mfma_f32_16x16x32_f16 v[120:123], v[188:191], v[132:135], v[120:123]
	s_barrier
	s_mov_b32 m0, s15
	s_add_u32 s74, s20, s4
	s_addc_u32 s75, s21, s5
	ds_read_b128 v[132:135], v244 offset:16384
	ds_read_b128 v[136:139], v244 offset:17408
	ds_read_b128 v[140:143], v244 offset:18432
	ds_read_b128 v[148:151], v244 offset:19456
	ds_read_b128 v[152:155], v244 offset:20480
	ds_read_b128 v[156:159], v244 offset:21504
	ds_read_b128 v[160:163], v244 offset:22528
	ds_read_b128 v[172:175], v244 offset:23552
	global_load_lds_dwordx4 v204, s[20:21]
	s_mov_b32 m0, s25
	s_nop 0
	global_load_lds_dwordx4 v208, s[20:21]
	s_barrier
	s_waitcnt lgkmcnt(0)
	v_mfma_f32_16x16x32_f16 v[60:63], v[80:83], v[132:135], v[60:63]
	v_mfma_f32_16x16x32_f16 v[56:59], v[96:99], v[132:135], v[56:59]
	v_mfma_f32_16x16x32_f16 v[44:47], v[80:83], v[140:143], v[44:47]
	v_mfma_f32_16x16x32_f16 v[40:43], v[96:99], v[140:143], v[40:43]
	v_mfma_f32_16x16x32_f16 v[28:31], v[80:83], v[152:155], v[28:31]
	v_mfma_f32_16x16x32_f16 v[24:27], v[96:99], v[152:155], v[24:27]
	v_mfma_f32_16x16x32_f16 v[12:15], v[80:83], v[160:163], v[12:15]
	v_mfma_f32_16x16x32_f16 v[8:11], v[96:99], v[160:163], v[8:11]
	v_mfma_f32_16x16x32_f16 v[60:63], v[88:91], v[136:139], v[60:63]
	v_mfma_f32_16x16x32_f16 v[56:59], v[100:103], v[136:139], v[56:59]
	v_mfma_f32_16x16x32_f16 v[44:47], v[88:91], v[148:151], v[44:47]
	v_mfma_f32_16x16x32_f16 v[40:43], v[100:103], v[148:151], v[40:43]
	v_mfma_f32_16x16x32_f16 v[28:31], v[88:91], v[156:159], v[28:31]
	v_mfma_f32_16x16x32_f16 v[24:27], v[100:103], v[156:159], v[24:27]
	v_mfma_f32_16x16x32_f16 v[12:15], v[88:91], v[172:175], v[12:15]
	v_mfma_f32_16x16x32_f16 v[8:11], v[100:103], v[172:175], v[8:11]
	s_barrier
	s_add_u32 s82, s18, 0x80000
	s_addc_u32 s83, s19, 0
	s_add_i32 s81, s76, s24
	s_mov_b32 m0, s81
	s_nop 0
	global_load_lds_dwordx4 v206, s[82:83]
	s_add_i32 m0, s81, 0x2000
	s_nop 0
	global_load_lds_dwordx4 v210, s[82:83]
	s_waitcnt vmcnt(6)
	s_barrier
	v_mfma_f32_16x16x32_f16 v[52:55], v[176:179], v[132:135], v[52:55]
	v_mfma_f32_16x16x32_f16 v[48:51], v[184:187], v[132:135], v[48:51]
	v_mfma_f32_16x16x32_f16 v[36:39], v[176:179], v[140:143], v[36:39]
	v_mfma_f32_16x16x32_f16 v[32:35], v[184:187], v[140:143], v[32:35]
	v_mfma_f32_16x16x32_f16 v[20:23], v[176:179], v[152:155], v[20:23]
	v_mfma_f32_16x16x32_f16 v[16:19], v[184:187], v[152:155], v[16:19]
	v_mfma_f32_16x16x32_f16 v[4:7], v[176:179], v[160:163], v[4:7]
	v_mfma_f32_16x16x32_f16 v[0:3], v[184:187], v[160:163], v[0:3]
	v_mfma_f32_16x16x32_f16 v[52:55], v[180:183], v[136:139], v[52:55]
	v_mfma_f32_16x16x32_f16 v[48:51], v[188:191], v[136:139], v[48:51]
	v_mfma_f32_16x16x32_f16 v[36:39], v[180:183], v[148:151], v[36:39]
	v_mfma_f32_16x16x32_f16 v[32:35], v[188:191], v[148:151], v[32:35]
	v_mfma_f32_16x16x32_f16 v[20:23], v[180:183], v[156:159], v[20:23]
	v_mfma_f32_16x16x32_f16 v[16:19], v[188:191], v[156:159], v[16:19]
	v_mfma_f32_16x16x32_f16 v[4:7], v[180:183], v[172:175], v[4:7]
	v_mfma_f32_16x16x32_f16 v[0:3], v[188:191], v[172:175], v[0:3]
	s_barrier
	s_add_i32 s81, 0, 0x18000
	v_add_u32_e32 v100, s81, v241
	ds_read_b128 v[80:83], v100
	ds_read_b128 v[88:91], v100 offset:1024
	ds_read_b128 v[96:99], v100 offset:2048
	ds_read_b128 v[100:103], v100 offset:3072
	s_add_u32 s20, s20, 0x80000
	s_addc_u32 s21, s21, 0
	s_mov_b32 m0, s26
	ds_read_b128 v[132:135], v244 offset:32768
	ds_read_b128 v[136:139], v244 offset:33792
	ds_read_b128 v[148:151], v244 offset:34816
	ds_read_b128 v[152:155], v244 offset:35840
	ds_read_b128 v[156:159], v244 offset:36864
	ds_read_b128 v[160:163], v244 offset:37888
	ds_read_b128 v[172:175], v244 offset:38912
	ds_read_b128 v[176:179], v244 offset:39936
	global_load_lds_dwordx4 v204, s[20:21]
	s_mov_b32 m0, s27
	s_nop 0
	global_load_lds_dwordx4 v208, s[20:21]
	s_waitcnt lgkmcnt(8)
	s_barrier
	s_waitcnt lgkmcnt(0)
	v_mfma_f32_16x16x32_f16 v[140:143], v[80:83], v[132:135], v[168:171]
	v_mfma_f32_16x16x32_f16 v[168:171], v[88:91], v[136:139], v[140:143]
	v_add_u32_e32 v192, 0x1c000, v241
	ds_read_b128 v[180:183], v192
	v_mfma_f32_16x16x32_f16 v[140:143], v[96:99], v[132:135], v[164:167]
	v_mfma_f32_16x16x32_f16 v[128:131], v[80:83], v[148:151], v[128:131]
	v_mfma_f32_16x16x32_f16 v[124:127], v[96:99], v[148:151], v[124:127]
	ds_read_b128 v[184:187], v192 offset:1024
	v_mfma_f32_16x16x32_f16 v[108:111], v[80:83], v[156:159], v[108:111]
	v_mfma_f32_16x16x32_f16 v[104:107], v[96:99], v[156:159], v[104:107]
	v_mfma_f32_16x16x32_f16 v[76:79], v[80:83], v[172:175], v[76:79]
	ds_read_b128 v[188:191], v192 offset:2048
	v_mfma_f32_16x16x32_f16 v[72:75], v[96:99], v[172:175], v[72:75]
	v_mfma_f32_16x16x32_f16 v[164:167], v[100:103], v[136:139], v[140:143]
	v_mfma_f32_16x16x32_f16 v[128:131], v[88:91], v[152:155], v[128:131]
	ds_read_b128 v[192:195], v192 offset:3072
	v_mfma_f32_16x16x32_f16 v[124:127], v[100:103], v[152:155], v[124:127]
	v_mfma_f32_16x16x32_f16 v[108:111], v[88:91], v[160:163], v[108:111]
	v_mfma_f32_16x16x32_f16 v[104:107], v[100:103], v[160:163], v[104:107]
	v_mfma_f32_16x16x32_f16 v[76:79], v[88:91], v[176:179], v[76:79]
	v_mfma_f32_16x16x32_f16 v[72:75], v[100:103], v[176:179], v[72:75]
	s_barrier
	s_add_i32 s20, 0, 0x1c000
	s_add_i32 s21, s81, s24
	s_mov_b32 m0, s21
	s_nop 0
	global_load_lds_dwordx4 v206, s[72:73]
	s_add_i32 m0, s21, 0x2000
	s_nop 0
	global_load_lds_dwordx4 v210, s[72:73]
	s_barrier
	s_waitcnt lgkmcnt(0)
	v_mfma_f32_16x16x32_f16 v[140:143], v[180:183], v[132:135], v[144:147]
	v_mfma_f32_16x16x32_f16 v[120:123], v[188:191], v[132:135], v[120:123]
	v_mfma_f32_16x16x32_f16 v[116:119], v[180:183], v[148:151], v[116:119]
	v_mfma_f32_16x16x32_f16 v[112:115], v[188:191], v[148:151], v[112:115]
	v_mfma_f32_16x16x32_f16 v[92:95], v[180:183], v[156:159], v[92:95]
	v_mfma_f32_16x16x32_f16 v[84:87], v[188:191], v[156:159], v[84:87]
	v_mfma_f32_16x16x32_f16 v[68:71], v[180:183], v[172:175], v[68:71]
	v_mfma_f32_16x16x32_f16 v[64:67], v[188:191], v[172:175], v[64:67]
	v_mfma_f32_16x16x32_f16 v[144:147], v[184:187], v[136:139], v[140:143]
	v_mfma_f32_16x16x32_f16 v[140:143], v[192:195], v[136:139], v[120:123]
	v_mfma_f32_16x16x32_f16 v[116:119], v[184:187], v[152:155], v[116:119]
	v_mfma_f32_16x16x32_f16 v[112:115], v[192:195], v[152:155], v[112:115]
	v_mfma_f32_16x16x32_f16 v[92:95], v[184:187], v[160:163], v[92:95]
	v_mfma_f32_16x16x32_f16 v[84:87], v[192:195], v[160:163], v[84:87]
	v_mfma_f32_16x16x32_f16 v[68:71], v[184:187], v[176:179], v[68:71]
	v_mfma_f32_16x16x32_f16 v[64:67], v[192:195], v[176:179], v[64:67]
	s_barrier
	s_mov_b32 m0, s35
	ds_read_b128 v[120:123], v244 offset:49152
	ds_read_b128 v[132:135], v244 offset:50176
	ds_read_b128 v[136:139], v244 offset:51200
	ds_read_b128 v[148:151], v244 offset:52224
	ds_read_b128 v[152:155], v244 offset:53248
	ds_read_b128 v[156:159], v244 offset:54272
	ds_read_b128 v[160:163], v244 offset:55296
	ds_read_b128 v[172:175], v244 offset:56320
	global_load_lds_dwordx4 v204, s[74:75]
	s_mov_b32 m0, s68
	s_nop 0
	global_load_lds_dwordx4 v208, s[74:75]
	s_barrier
	s_waitcnt lgkmcnt(0)
	v_mfma_f32_16x16x32_f16 v[60:63], v[80:83], v[120:123], v[60:63]
	v_mfma_f32_16x16x32_f16 v[56:59], v[96:99], v[120:123], v[56:59]
	v_mfma_f32_16x16x32_f16 v[44:47], v[80:83], v[136:139], v[44:47]
	v_mfma_f32_16x16x32_f16 v[40:43], v[96:99], v[136:139], v[40:43]
	v_mfma_f32_16x16x32_f16 v[28:31], v[80:83], v[152:155], v[28:31]
	v_mfma_f32_16x16x32_f16 v[24:27], v[96:99], v[152:155], v[24:27]
	v_mfma_f32_16x16x32_f16 v[12:15], v[80:83], v[160:163], v[12:15]
	v_mfma_f32_16x16x32_f16 v[8:11], v[96:99], v[160:163], v[8:11]
	v_mfma_f32_16x16x32_f16 v[60:63], v[88:91], v[132:135], v[60:63]
	v_mfma_f32_16x16x32_f16 v[56:59], v[100:103], v[132:135], v[56:59]
	v_mfma_f32_16x16x32_f16 v[44:47], v[88:91], v[148:151], v[44:47]
	v_mfma_f32_16x16x32_f16 v[40:43], v[100:103], v[148:151], v[40:43]
	v_mfma_f32_16x16x32_f16 v[28:31], v[88:91], v[156:159], v[28:31]
	v_mfma_f32_16x16x32_f16 v[24:27], v[100:103], v[156:159], v[24:27]
	v_mfma_f32_16x16x32_f16 v[12:15], v[88:91], v[172:175], v[12:15]
	v_mfma_f32_16x16x32_f16 v[8:11], v[100:103], v[172:175], v[8:11]
	s_barrier
	s_add_u32 s18, s18, 0x80080
	s_addc_u32 s19, s19, 0
	s_add_i32 s20, s20, s24
	s_mov_b32 m0, s20
	s_nop 0
	global_load_lds_dwordx4 v206, s[18:19]
	s_add_i32 m0, s20, 0x2000
	s_nop 0
	global_load_lds_dwordx4 v210, s[18:19]
	s_waitcnt vmcnt(6)
	s_barrier
	v_mfma_f32_16x16x32_f16 v[52:55], v[180:183], v[120:123], v[52:55]
	v_mfma_f32_16x16x32_f16 v[48:51], v[188:191], v[120:123], v[48:51]
	v_mfma_f32_16x16x32_f16 v[36:39], v[180:183], v[136:139], v[36:39]
	v_mfma_f32_16x16x32_f16 v[32:35], v[188:191], v[136:139], v[32:35]
	v_mfma_f32_16x16x32_f16 v[20:23], v[180:183], v[152:155], v[20:23]
	v_mfma_f32_16x16x32_f16 v[16:19], v[188:191], v[152:155], v[16:19]
	v_mfma_f32_16x16x32_f16 v[4:7], v[180:183], v[160:163], v[4:7]
	v_mfma_f32_16x16x32_f16 v[0:3], v[188:191], v[160:163], v[0:3]
	v_mfma_f32_16x16x32_f16 v[52:55], v[184:187], v[132:135], v[52:55]
	v_mfma_f32_16x16x32_f16 v[48:51], v[192:195], v[132:135], v[48:51]
	v_mfma_f32_16x16x32_f16 v[36:39], v[184:187], v[148:151], v[36:39]
	v_mfma_f32_16x16x32_f16 v[32:35], v[192:195], v[148:151], v[32:35]
	v_mfma_f32_16x16x32_f16 v[20:23], v[184:187], v[156:159], v[20:23]
	v_mfma_f32_16x16x32_f16 v[16:19], v[192:195], v[156:159], v[16:19]
	v_mfma_f32_16x16x32_f16 v[4:7], v[184:187], v[172:175], v[4:7]
	v_mfma_f32_16x16x32_f16 v[0:3], v[192:195], v[172:175], v[0:3]
	s_barrier
	s_add_i32 s80, s80, 2
	s_add_u32 s16, s16, 0x100
	s_addc_u32 s17, s17, 0
	s_add_u32 s78, s78, 0x100
	s_addc_u32 s79, s79, 0
	s_cmp_gt_u32 s80, 29
	s_cbranch_scc0 .LBB0_647
	s_setprio 0
	s_lshl_b32 s7, s14, 8
	s_add_i32 s9, s7, 0xffffe000
	s_lshr_b32 s9, s9, 11
	s_mulk_i32 s9, 0x1800
	s_addk_i32 s9, 0x1800
	s_cmp_gt_i32 s14, 31
	s_cselect_b32 s16, s9, 0
	s_ashr_i32 s17, s16, 31
	v_lshl_or_b32 v120, s30, 8, v242
	s_lshl_b64 s[16:17], s[16:17], 2
	s_add_u32 s16, s29, s16
	v_ashrrev_i32_e32 v121, 31, v120
	v_add_u32_e32 v122, s7, v240
	s_addc_u32 s17, s34, s17
	v_lshlrev_b64 v[220:221], 1, v[120:121]
	v_ashrrev_i32_e32 v123, 31, v122
	v_lshl_add_u64 v[88:89], v[120:121], 2, s[16:17]
	v_lshl_add_u64 v[120:121], s[40:41], 0, v[220:221]
	v_lshlrev_b64 v[236:237], 12, v[122:123]
	v_lshl_add_u64 v[132:133], v[120:121], 0, v[236:237]
	global_load_dwordx4 v[96:99], v[88:89], off offset:16
	global_load_dwordx4 v[100:103], v[88:89], off
	global_load_dwordx4 v[80:83], v[88:89], off offset:528
	s_nop 0
	global_load_dwordx4 v[88:91], v[88:89], off offset:512
	s_nop 0
	global_load_dwordx4 v[246:249], v[132:133], off nt
	global_load_dwordx4 v[200:203], v[132:133], off offset:256 nt
	v_or_b32_e32 v132, 16, v122
	v_ashrrev_i32_e32 v133, 31, v132
	v_lshlrev_b64 v[234:235], 12, v[132:133]
	v_lshl_add_u64 v[132:133], v[120:121], 0, v[234:235]
	global_load_dwordx4 v[196:199], v[132:133], off nt
	global_load_dwordx4 v[192:195], v[132:133], off offset:256 nt
	v_or_b32_e32 v132, 32, v122
	v_ashrrev_i32_e32 v133, 31, v132
	v_lshlrev_b64 v[232:233], 12, v[132:133]
	v_lshl_add_u64 v[132:133], v[120:121], 0, v[232:233]
	global_load_dwordx4 v[188:191], v[132:133], off nt
	global_load_dwordx4 v[184:187], v[132:133], off offset:256 nt
	v_or_b32_e32 v122, 48, v122
	v_ashrrev_i32_e32 v123, 31, v122
	v_lshlrev_b64 v[230:231], 12, v[122:123]
	v_lshl_add_u64 v[122:123], v[120:121], 0, v[230:231]
	global_load_dwordx4 v[180:183], v[122:123], off nt
	global_load_dwordx4 v[176:179], v[122:123], off offset:256 nt
	s_mov_b64 s[16:17], 0x80000
	v_lshl_add_u64 v[228:229], v[236:237], 0, s[16:17]
	v_lshl_add_u64 v[122:123], v[120:121], 0, v[228:229]
	global_load_dwordx4 v[172:175], v[122:123], off nt
	global_load_dwordx4 v[160:163], v[122:123], off offset:256 nt
	s_mov_b64 s[16:17], 0x90000
	v_lshl_add_u64 v[226:227], v[236:237], 0, s[16:17]
	v_lshl_add_u64 v[122:123], v[120:121], 0, v[226:227]
	global_load_dwordx4 v[156:159], v[122:123], off nt
	global_load_dwordx4 v[152:155], v[122:123], off offset:256 nt
	s_mov_b64 s[16:17], 0xa0000
	v_lshl_add_u64 v[224:225], v[236:237], 0, s[16:17]
	v_lshl_add_u64 v[122:123], v[120:121], 0, v[224:225]
	global_load_dwordx4 v[148:151], v[122:123], off nt
	global_load_dwordx4 v[136:139], v[122:123], off offset:256 nt
	s_mov_b64 s[16:17], 0xb0000
	v_lshl_add_u64 v[222:223], v[236:237], 0, s[16:17]
	v_lshl_add_u64 v[120:121], v[120:121], 0, v[222:223]
	global_load_dwordx4 v[132:135], v[120:121], off nt
	s_nop 0
	global_load_dwordx4 v[120:123], v[120:121], off offset:256 nt
	s_and_b64 vcc, exec, s[2:3]
	s_mov_b32 s30, s6
	s_mov_b32 s14, s8
	s_mov_b64 s[18:19], s[12:13]
	s_mov_b64 s[16:17], s[10:11]
	s_waitcnt vmcnt(0)
	v_cvt_f32_f16_e32 v250, v246
	v_cvt_f32_f16_sdwa v251, v246 dst_sel:DWORD dst_unused:UNUSED_PAD src0_sel:WORD_1
	v_pk_fma_f32 v[168:169], v[168:169], v[100:101], v[250:251]
	s_nop 0
	v_cvt_pk_f16_f32 v246, v168, v169
	v_cvt_f32_f16_e32 v168, v248
	v_cvt_f32_f16_sdwa v169, v248 dst_sel:DWORD dst_unused:UNUSED_PAD src0_sel:WORD_1
	v_pk_fma_f32 v[164:165], v[164:165], v[96:97], v[168:169]
	s_nop 0
	v_cvt_pk_f16_f32 v248, v164, v165
	v_cvt_f32_f16_e32 v164, v247
	v_cvt_f32_f16_sdwa v165, v247 dst_sel:DWORD dst_unused:UNUSED_PAD src0_sel:WORD_1
	v_pk_fma_f32 v[164:165], v[170:171], v[102:103], v[164:165]
	s_nop 0
	v_cvt_pk_f16_f32 v247, v164, v165
	v_cvt_f32_f16_e32 v164, v249
	v_cvt_f32_f16_sdwa v165, v249 dst_sel:DWORD dst_unused:UNUSED_PAD src0_sel:WORD_1
	v_pk_fma_f32 v[164:165], v[166:167], v[98:99], v[164:165]
	s_nop 0
	v_cvt_pk_f16_f32 v249, v164, v165
	v_lshl_add_u64 v[164:165], s[0:1], 0, v[236:237]
	v_lshl_add_u64 v[168:169], v[164:165], 0, v[220:221]
	v_cvt_f32_f16_e32 v164, v200
	v_cvt_f32_f16_sdwa v165, v200 dst_sel:DWORD dst_unused:UNUSED_PAD src0_sel:WORD_1
	global_store_dwordx4 v[168:169], v[246:249], off
	v_pk_fma_f32 v[144:145], v[144:145], v[88:89], v[164:165]
	s_nop 0
	v_cvt_pk_f16_f32 v164, v144, v145
	v_cvt_f32_f16_e32 v144, v202
	v_cvt_f32_f16_sdwa v145, v202 dst_sel:DWORD dst_unused:UNUSED_PAD src0_sel:WORD_1
	v_pk_fma_f32 v[140:141], v[140:141], v[80:81], v[144:145]
	s_nop 0
	v_cvt_pk_f16_f32 v166, v140, v141
	v_cvt_f32_f16_e32 v140, v201
	v_cvt_f32_f16_sdwa v141, v201 dst_sel:DWORD dst_unused:UNUSED_PAD src0_sel:WORD_1
	v_pk_fma_f32 v[140:141], v[146:147], v[90:91], v[140:141]
	s_nop 0
	v_cvt_pk_f16_f32 v165, v140, v141
	v_cvt_f32_f16_e32 v140, v203
	v_cvt_f32_f16_sdwa v141, v203 dst_sel:DWORD dst_unused:UNUSED_PAD src0_sel:WORD_1
	v_pk_fma_f32 v[140:141], v[142:143], v[82:83], v[140:141]
	s_nop 0
	v_cvt_pk_f16_f32 v167, v140, v141
	v_cvt_f32_f16_e32 v140, v196
	v_cvt_f32_f16_sdwa v141, v196 dst_sel:DWORD dst_unused:UNUSED_PAD src0_sel:WORD_1
	global_store_dwordx4 v[168:169], v[164:167], off offset:256
	v_pk_fma_f32 v[128:129], v[128:129], v[100:101], v[140:141]
	s_nop 0
	v_cvt_pk_f16_f32 v140, v128, v129
	v_cvt_f32_f16_e32 v128, v198
	v_cvt_f32_f16_sdwa v129, v198 dst_sel:DWORD dst_unused:UNUSED_PAD src0_sel:WORD_1
	v_pk_fma_f32 v[124:125], v[124:125], v[96:97], v[128:129]
	s_nop 0
	v_cvt_pk_f16_f32 v142, v124, v125
	v_cvt_f32_f16_e32 v124, v197
	v_cvt_f32_f16_sdwa v125, v197 dst_sel:DWORD dst_unused:UNUSED_PAD src0_sel:WORD_1
	v_pk_fma_f32 v[124:125], v[130:131], v[102:103], v[124:125]
	s_nop 0
	v_cvt_pk_f16_f32 v141, v124, v125
	v_cvt_f32_f16_e32 v124, v199
	v_cvt_f32_f16_sdwa v125, v199 dst_sel:DWORD dst_unused:UNUSED_PAD src0_sel:WORD_1
	v_pk_fma_f32 v[124:125], v[126:127], v[98:99], v[124:125]
	s_nop 0
	v_cvt_pk_f16_f32 v143, v124, v125
	v_lshl_add_u64 v[124:125], s[0:1], 0, v[234:235]
	v_lshl_add_u64 v[128:129], v[124:125], 0, v[220:221]
	v_cvt_f32_f16_e32 v124, v192
	v_cvt_f32_f16_sdwa v125, v192 dst_sel:DWORD dst_unused:UNUSED_PAD src0_sel:WORD_1
	global_store_dwordx4 v[128:129], v[140:143], off
	v_pk_fma_f32 v[116:117], v[116:117], v[88:89], v[124:125]
	s_nop 0
	v_cvt_pk_f16_f32 v124, v116, v117
	v_cvt_f32_f16_e32 v116, v194
	v_cvt_f32_f16_sdwa v117, v194 dst_sel:DWORD dst_unused:UNUSED_PAD src0_sel:WORD_1
	v_pk_fma_f32 v[112:113], v[112:113], v[80:81], v[116:117]
	s_nop 0
	v_cvt_pk_f16_f32 v126, v112, v113
	v_cvt_f32_f16_e32 v112, v193
	v_cvt_f32_f16_sdwa v113, v193 dst_sel:DWORD dst_unused:UNUSED_PAD src0_sel:WORD_1
	v_pk_fma_f32 v[112:113], v[118:119], v[90:91], v[112:113]
	s_nop 0
	v_cvt_pk_f16_f32 v125, v112, v113
	v_cvt_f32_f16_e32 v112, v195
	v_cvt_f32_f16_sdwa v113, v195 dst_sel:DWORD dst_unused:UNUSED_PAD src0_sel:WORD_1
	v_pk_fma_f32 v[112:113], v[114:115], v[82:83], v[112:113]
	s_nop 0
	v_cvt_pk_f16_f32 v127, v112, v113
	v_cvt_f32_f16_e32 v112, v188
	v_cvt_f32_f16_sdwa v113, v188 dst_sel:DWORD dst_unused:UNUSED_PAD src0_sel:WORD_1
	global_store_dwordx4 v[128:129], v[124:127], off offset:256
	v_pk_fma_f32 v[108:109], v[108:109], v[100:101], v[112:113]
	s_nop 0
	v_cvt_pk_f16_f32 v112, v108, v109
	v_cvt_f32_f16_e32 v108, v190
	v_cvt_f32_f16_sdwa v109, v190 dst_sel:DWORD dst_unused:UNUSED_PAD src0_sel:WORD_1
	v_pk_fma_f32 v[104:105], v[104:105], v[96:97], v[108:109]
	s_nop 0
	v_cvt_pk_f16_f32 v114, v104, v105
	v_cvt_f32_f16_e32 v104, v189
	v_cvt_f32_f16_sdwa v105, v189 dst_sel:DWORD dst_unused:UNUSED_PAD src0_sel:WORD_1
	v_pk_fma_f32 v[104:105], v[110:111], v[102:103], v[104:105]
	s_nop 0
	v_cvt_pk_f16_f32 v113, v104, v105
	v_cvt_f32_f16_e32 v104, v191
	v_cvt_f32_f16_sdwa v105, v191 dst_sel:DWORD dst_unused:UNUSED_PAD src0_sel:WORD_1
	v_pk_fma_f32 v[104:105], v[106:107], v[98:99], v[104:105]
	s_nop 0
	v_cvt_pk_f16_f32 v115, v104, v105
	v_lshl_add_u64 v[104:105], s[0:1], 0, v[232:233]
	v_lshl_add_u64 v[108:109], v[104:105], 0, v[220:221]
	v_cvt_f32_f16_e32 v104, v184
	v_cvt_f32_f16_sdwa v105, v184 dst_sel:DWORD dst_unused:UNUSED_PAD src0_sel:WORD_1
	global_store_dwordx4 v[108:109], v[112:115], off
	v_pk_fma_f32 v[92:93], v[92:93], v[88:89], v[104:105]
	s_nop 0
	v_cvt_pk_f16_f32 v104, v92, v93
	v_cvt_f32_f16_e32 v92, v186
	v_cvt_f32_f16_sdwa v93, v186 dst_sel:DWORD dst_unused:UNUSED_PAD src0_sel:WORD_1
	v_pk_fma_f32 v[84:85], v[84:85], v[80:81], v[92:93]
	s_nop 0
	v_cvt_pk_f16_f32 v106, v84, v85
	v_cvt_f32_f16_e32 v84, v185
	v_cvt_f32_f16_sdwa v85, v185 dst_sel:DWORD dst_unused:UNUSED_PAD src0_sel:WORD_1
	v_pk_fma_f32 v[84:85], v[94:95], v[90:91], v[84:85]
	s_nop 0
	v_cvt_pk_f16_f32 v105, v84, v85
	v_cvt_f32_f16_e32 v84, v187
	v_cvt_f32_f16_sdwa v85, v187 dst_sel:DWORD dst_unused:UNUSED_PAD src0_sel:WORD_1
	v_pk_fma_f32 v[84:85], v[86:87], v[82:83], v[84:85]
	s_nop 0
	v_cvt_pk_f16_f32 v107, v84, v85
	v_cvt_f32_f16_e32 v84, v180
	v_cvt_f32_f16_sdwa v85, v180 dst_sel:DWORD dst_unused:UNUSED_PAD src0_sel:WORD_1
	global_store_dwordx4 v[108:109], v[104:107], off offset:256
	v_pk_fma_f32 v[76:77], v[76:77], v[100:101], v[84:85]
	s_nop 0
	v_cvt_pk_f16_f32 v84, v76, v77
	v_cvt_f32_f16_e32 v76, v182
	v_cvt_f32_f16_sdwa v77, v182 dst_sel:DWORD dst_unused:UNUSED_PAD src0_sel:WORD_1
	v_pk_fma_f32 v[72:73], v[72:73], v[96:97], v[76:77]
	s_nop 0
	v_cvt_pk_f16_f32 v86, v72, v73
	v_cvt_f32_f16_e32 v72, v181
	v_cvt_f32_f16_sdwa v73, v181 dst_sel:DWORD dst_unused:UNUSED_PAD src0_sel:WORD_1
	v_pk_fma_f32 v[72:73], v[78:79], v[102:103], v[72:73]
	s_nop 0
	v_cvt_pk_f16_f32 v85, v72, v73
	v_cvt_f32_f16_e32 v72, v183
	v_cvt_f32_f16_sdwa v73, v183 dst_sel:DWORD dst_unused:UNUSED_PAD src0_sel:WORD_1
	v_pk_fma_f32 v[72:73], v[74:75], v[98:99], v[72:73]
	s_nop 0
	v_cvt_pk_f16_f32 v87, v72, v73
	v_lshl_add_u64 v[72:73], s[0:1], 0, v[230:231]
	v_lshl_add_u64 v[76:77], v[72:73], 0, v[220:221]
	v_cvt_f32_f16_e32 v72, v176
	v_cvt_f32_f16_sdwa v73, v176 dst_sel:DWORD dst_unused:UNUSED_PAD src0_sel:WORD_1
	global_store_dwordx4 v[76:77], v[84:87], off
	v_pk_fma_f32 v[68:69], v[68:69], v[88:89], v[72:73]
	s_nop 0
	v_cvt_pk_f16_f32 v72, v68, v69
	v_cvt_f32_f16_e32 v68, v178
	v_cvt_f32_f16_sdwa v69, v178 dst_sel:DWORD dst_unused:UNUSED_PAD src0_sel:WORD_1
	v_pk_fma_f32 v[64:65], v[64:65], v[80:81], v[68:69]
	s_nop 0
	v_cvt_pk_f16_f32 v74, v64, v65
	v_cvt_f32_f16_e32 v64, v177
	v_cvt_f32_f16_sdwa v65, v177 dst_sel:DWORD dst_unused:UNUSED_PAD src0_sel:WORD_1
	v_pk_fma_f32 v[64:65], v[70:71], v[90:91], v[64:65]
	s_nop 0
	v_cvt_pk_f16_f32 v73, v64, v65
	v_cvt_f32_f16_e32 v64, v179
	v_cvt_f32_f16_sdwa v65, v179 dst_sel:DWORD dst_unused:UNUSED_PAD src0_sel:WORD_1
	v_pk_fma_f32 v[64:65], v[66:67], v[82:83], v[64:65]
	s_nop 0
	v_cvt_pk_f16_f32 v75, v64, v65
	v_cvt_f32_f16_e32 v64, v172
	v_cvt_f32_f16_sdwa v65, v172 dst_sel:DWORD dst_unused:UNUSED_PAD src0_sel:WORD_1
	global_store_dwordx4 v[76:77], v[72:75], off offset:256
	v_pk_fma_f32 v[60:61], v[60:61], v[100:101], v[64:65]
	s_nop 0
	v_cvt_pk_f16_f32 v64, v60, v61
	v_cvt_f32_f16_e32 v60, v174
	v_cvt_f32_f16_sdwa v61, v174 dst_sel:DWORD dst_unused:UNUSED_PAD src0_sel:WORD_1
	v_pk_fma_f32 v[56:57], v[56:57], v[96:97], v[60:61]
	s_nop 0
	v_cvt_pk_f16_f32 v66, v56, v57
	v_cvt_f32_f16_e32 v56, v173
	v_cvt_f32_f16_sdwa v57, v173 dst_sel:DWORD dst_unused:UNUSED_PAD src0_sel:WORD_1
	v_pk_fma_f32 v[56:57], v[62:63], v[102:103], v[56:57]
	s_nop 0
	v_cvt_pk_f16_f32 v65, v56, v57
	v_cvt_f32_f16_e32 v56, v175
	v_cvt_f32_f16_sdwa v57, v175 dst_sel:DWORD dst_unused:UNUSED_PAD src0_sel:WORD_1
	v_pk_fma_f32 v[56:57], v[58:59], v[98:99], v[56:57]
	s_nop 0
	v_cvt_pk_f16_f32 v67, v56, v57
	v_lshl_add_u64 v[56:57], s[0:1], 0, v[228:229]
	v_lshl_add_u64 v[60:61], v[56:57], 0, v[220:221]
	v_cvt_f32_f16_e32 v56, v160
	v_cvt_f32_f16_sdwa v57, v160 dst_sel:DWORD dst_unused:UNUSED_PAD src0_sel:WORD_1
	global_store_dwordx4 v[60:61], v[64:67], off
	v_pk_fma_f32 v[52:53], v[52:53], v[88:89], v[56:57]
	s_nop 0
	v_cvt_pk_f16_f32 v56, v52, v53
	v_cvt_f32_f16_e32 v52, v162
	v_cvt_f32_f16_sdwa v53, v162 dst_sel:DWORD dst_unused:UNUSED_PAD src0_sel:WORD_1
	v_pk_fma_f32 v[48:49], v[48:49], v[80:81], v[52:53]
	s_nop 0
	v_cvt_pk_f16_f32 v58, v48, v49
	v_cvt_f32_f16_e32 v48, v161
	v_cvt_f32_f16_sdwa v49, v161 dst_sel:DWORD dst_unused:UNUSED_PAD src0_sel:WORD_1
	v_pk_fma_f32 v[48:49], v[54:55], v[90:91], v[48:49]
	s_nop 0
	v_cvt_pk_f16_f32 v57, v48, v49
	v_cvt_f32_f16_e32 v48, v163
	v_cvt_f32_f16_sdwa v49, v163 dst_sel:DWORD dst_unused:UNUSED_PAD src0_sel:WORD_1
	v_pk_fma_f32 v[48:49], v[50:51], v[82:83], v[48:49]
	s_nop 0
	v_cvt_pk_f16_f32 v59, v48, v49
	v_cvt_f32_f16_e32 v48, v156
	v_cvt_f32_f16_sdwa v49, v156 dst_sel:DWORD dst_unused:UNUSED_PAD src0_sel:WORD_1
	global_store_dwordx4 v[60:61], v[56:59], off offset:256
	v_pk_fma_f32 v[44:45], v[44:45], v[100:101], v[48:49]
	s_nop 0
	v_cvt_pk_f16_f32 v48, v44, v45
	v_cvt_f32_f16_e32 v44, v158
	v_cvt_f32_f16_sdwa v45, v158 dst_sel:DWORD dst_unused:UNUSED_PAD src0_sel:WORD_1
	v_pk_fma_f32 v[40:41], v[40:41], v[96:97], v[44:45]
	s_nop 0
	v_cvt_pk_f16_f32 v50, v40, v41
	v_cvt_f32_f16_e32 v40, v157
	v_cvt_f32_f16_sdwa v41, v157 dst_sel:DWORD dst_unused:UNUSED_PAD src0_sel:WORD_1
	v_pk_fma_f32 v[40:41], v[46:47], v[102:103], v[40:41]
	s_nop 0
	v_cvt_pk_f16_f32 v49, v40, v41
	v_cvt_f32_f16_e32 v40, v159
	v_cvt_f32_f16_sdwa v41, v159 dst_sel:DWORD dst_unused:UNUSED_PAD src0_sel:WORD_1
	v_pk_fma_f32 v[40:41], v[42:43], v[98:99], v[40:41]
	s_nop 0
	v_cvt_pk_f16_f32 v51, v40, v41
	v_lshl_add_u64 v[40:41], s[0:1], 0, v[226:227]
	v_lshl_add_u64 v[44:45], v[40:41], 0, v[220:221]
	v_cvt_f32_f16_e32 v40, v152
	v_cvt_f32_f16_sdwa v41, v152 dst_sel:DWORD dst_unused:UNUSED_PAD src0_sel:WORD_1
	global_store_dwordx4 v[44:45], v[48:51], off
	v_pk_fma_f32 v[36:37], v[36:37], v[88:89], v[40:41]
	s_nop 0
	v_cvt_pk_f16_f32 v40, v36, v37
	v_cvt_f32_f16_e32 v36, v154
	v_cvt_f32_f16_sdwa v37, v154 dst_sel:DWORD dst_unused:UNUSED_PAD src0_sel:WORD_1
	v_pk_fma_f32 v[32:33], v[32:33], v[80:81], v[36:37]
	s_nop 0
	v_cvt_pk_f16_f32 v42, v32, v33
	v_cvt_f32_f16_e32 v32, v153
	v_cvt_f32_f16_sdwa v33, v153 dst_sel:DWORD dst_unused:UNUSED_PAD src0_sel:WORD_1
	v_pk_fma_f32 v[32:33], v[38:39], v[90:91], v[32:33]
	s_nop 0
	v_cvt_pk_f16_f32 v41, v32, v33
	v_cvt_f32_f16_e32 v32, v155
	v_cvt_f32_f16_sdwa v33, v155 dst_sel:DWORD dst_unused:UNUSED_PAD src0_sel:WORD_1
	v_pk_fma_f32 v[32:33], v[34:35], v[82:83], v[32:33]
	s_nop 0
	v_cvt_pk_f16_f32 v43, v32, v33
	v_cvt_f32_f16_e32 v32, v148
	v_cvt_f32_f16_sdwa v33, v148 dst_sel:DWORD dst_unused:UNUSED_PAD src0_sel:WORD_1
	global_store_dwordx4 v[44:45], v[40:43], off offset:256
	v_pk_fma_f32 v[28:29], v[28:29], v[100:101], v[32:33]
	s_nop 0
	v_cvt_pk_f16_f32 v32, v28, v29
	v_cvt_f32_f16_e32 v28, v150
	v_cvt_f32_f16_sdwa v29, v150 dst_sel:DWORD dst_unused:UNUSED_PAD src0_sel:WORD_1
	v_pk_fma_f32 v[24:25], v[24:25], v[96:97], v[28:29]
	s_nop 0
	v_cvt_pk_f16_f32 v34, v24, v25
	v_cvt_f32_f16_e32 v24, v149
	v_cvt_f32_f16_sdwa v25, v149 dst_sel:DWORD dst_unused:UNUSED_PAD src0_sel:WORD_1
	v_pk_fma_f32 v[24:25], v[30:31], v[102:103], v[24:25]
	s_nop 0
	v_cvt_pk_f16_f32 v33, v24, v25
	v_cvt_f32_f16_e32 v24, v151
	v_cvt_f32_f16_sdwa v25, v151 dst_sel:DWORD dst_unused:UNUSED_PAD src0_sel:WORD_1
	v_pk_fma_f32 v[24:25], v[26:27], v[98:99], v[24:25]
	s_nop 0
	v_cvt_pk_f16_f32 v35, v24, v25
	v_lshl_add_u64 v[24:25], s[0:1], 0, v[224:225]
	v_lshl_add_u64 v[28:29], v[24:25], 0, v[220:221]
	v_cvt_f32_f16_e32 v24, v136
	v_cvt_f32_f16_sdwa v25, v136 dst_sel:DWORD dst_unused:UNUSED_PAD src0_sel:WORD_1
	global_store_dwordx4 v[28:29], v[32:35], off
	v_pk_fma_f32 v[20:21], v[20:21], v[88:89], v[24:25]
	s_nop 0
	v_cvt_pk_f16_f32 v24, v20, v21
	v_cvt_f32_f16_e32 v20, v138
	v_cvt_f32_f16_sdwa v21, v138 dst_sel:DWORD dst_unused:UNUSED_PAD src0_sel:WORD_1
	v_pk_fma_f32 v[16:17], v[16:17], v[80:81], v[20:21]
	s_nop 0
	v_cvt_pk_f16_f32 v26, v16, v17
	v_cvt_f32_f16_e32 v16, v137
	v_cvt_f32_f16_sdwa v17, v137 dst_sel:DWORD dst_unused:UNUSED_PAD src0_sel:WORD_1
	v_pk_fma_f32 v[16:17], v[22:23], v[90:91], v[16:17]
	s_nop 0
	v_cvt_pk_f16_f32 v25, v16, v17
	v_cvt_f32_f16_e32 v16, v139
	v_cvt_f32_f16_sdwa v17, v139 dst_sel:DWORD dst_unused:UNUSED_PAD src0_sel:WORD_1
	v_pk_fma_f32 v[16:17], v[18:19], v[82:83], v[16:17]
	s_nop 0
	v_cvt_pk_f16_f32 v27, v16, v17
	v_cvt_f32_f16_e32 v16, v132
	v_cvt_f32_f16_sdwa v17, v132 dst_sel:DWORD dst_unused:UNUSED_PAD src0_sel:WORD_1
	global_store_dwordx4 v[28:29], v[24:27], off offset:256
	v_pk_fma_f32 v[12:13], v[12:13], v[100:101], v[16:17]
	s_nop 0
	v_cvt_pk_f16_f32 v16, v12, v13
	v_cvt_f32_f16_e32 v12, v134
	v_cvt_f32_f16_sdwa v13, v134 dst_sel:DWORD dst_unused:UNUSED_PAD src0_sel:WORD_1
	v_pk_fma_f32 v[8:9], v[8:9], v[96:97], v[12:13]
	s_nop 0
	v_cvt_pk_f16_f32 v18, v8, v9
	v_cvt_f32_f16_e32 v8, v133
	v_cvt_f32_f16_sdwa v9, v133 dst_sel:DWORD dst_unused:UNUSED_PAD src0_sel:WORD_1
	v_pk_fma_f32 v[8:9], v[14:15], v[102:103], v[8:9]
	s_nop 0
	v_cvt_pk_f16_f32 v17, v8, v9
	v_cvt_f32_f16_e32 v8, v135
	v_cvt_f32_f16_sdwa v9, v135 dst_sel:DWORD dst_unused:UNUSED_PAD src0_sel:WORD_1
	v_pk_fma_f32 v[8:9], v[10:11], v[98:99], v[8:9]
	s_nop 0
	v_cvt_pk_f16_f32 v19, v8, v9
	v_lshl_add_u64 v[8:9], s[0:1], 0, v[222:223]
	v_lshl_add_u64 v[12:13], v[8:9], 0, v[220:221]
	v_cvt_f32_f16_e32 v8, v120
	v_cvt_f32_f16_sdwa v9, v120 dst_sel:DWORD dst_unused:UNUSED_PAD src0_sel:WORD_1
	global_store_dwordx4 v[12:13], v[16:19], off
	v_pk_fma_f32 v[4:5], v[4:5], v[88:89], v[8:9]
	s_nop 0
	v_cvt_pk_f16_f32 v8, v4, v5
	v_cvt_f32_f16_e32 v4, v122
	v_cvt_f32_f16_sdwa v5, v122 dst_sel:DWORD dst_unused:UNUSED_PAD src0_sel:WORD_1
	v_pk_fma_f32 v[0:1], v[0:1], v[80:81], v[4:5]
	s_nop 0
	v_cvt_pk_f16_f32 v10, v0, v1
	v_cvt_f32_f16_e32 v0, v121
	v_cvt_f32_f16_sdwa v1, v121 dst_sel:DWORD dst_unused:UNUSED_PAD src0_sel:WORD_1
	v_pk_fma_f32 v[0:1], v[6:7], v[90:91], v[0:1]
	s_nop 0
	v_cvt_pk_f16_f32 v9, v0, v1
	v_cvt_f32_f16_e32 v0, v123
	v_cvt_f32_f16_sdwa v1, v123 dst_sel:DWORD dst_unused:UNUSED_PAD src0_sel:WORD_1
	v_pk_fma_f32 v[0:1], v[2:3], v[82:83], v[0:1]
	s_nop 0
	v_cvt_pk_f16_f32 v11, v0, v1
	global_store_dwordx4 v[12:13], v[8:11], off offset:256
	s_cbranch_vccz .LBB0_640
	s_waitcnt vmcnt(0)
	s_cmpk_gt_u32 s22, 0xff
	s_cbranch_scc1 .LBB0_651
	s_barrier

.LBB0_1185:
	ds_read_b128 v[88:91], v243
	ds_read_b128 v[96:99], v243 offset:1024
	ds_read_b128 v[108:111], v243 offset:2048
	ds_read_b128 v[116:119], v243 offset:3072
	s_add_u32 s26, s24, 0xfff80080
	s_addc_u32 s27, s25, -1
	s_cmp_eq_u32 s64, 28
	s_cselect_b32 s29, s17, s27
	s_cselect_b32 s28, s31, s26
	s_cselect_b32 s27, s15, s63
	s_cselect_b32 s26, s61, s62
	s_add_i32 m0, s23, 0xc000
	ds_read_b128 v[128:131], v244
	ds_read_b128 v[136:139], v244 offset:1024
	ds_read_b128 v[144:147], v244 offset:2048
	ds_read_b128 v[148:151], v244 offset:3072
	ds_read_b128 v[152:155], v244 offset:4096
	ds_read_b128 v[164:167], v244 offset:5120
	ds_read_b128 v[168:171], v244 offset:6144
	ds_read_b128 v[172:175], v244 offset:7168
	global_load_lds_dwordx4 v212, s[24:25]
	s_add_i32 m0, s23, 0xe000
	s_nop 0
	global_load_lds_dwordx4 v214, s[24:25]
	s_waitcnt lgkmcnt(8)
	s_barrier
	s_waitcnt lgkmcnt(0)
	v_mfma_f32_16x16x32_f16 v[160:163], v[88:91], v[128:131], v[160:163]
	v_mfma_f32_16x16x32_f16 v[156:159], v[108:111], v[128:131], v[156:159]
	ds_read_b128 v[176:179], v245
	v_mfma_f32_16x16x32_f16 v[124:127], v[88:91], v[144:147], v[124:127]
	v_mfma_f32_16x16x32_f16 v[120:123], v[108:111], v[144:147], v[120:123]
	v_mfma_f32_16x16x32_f16 v[100:103], v[88:91], v[152:155], v[100:103]
	ds_read_b128 v[180:183], v245 offset:1024
	v_mfma_f32_16x16x32_f16 v[92:95], v[108:111], v[152:155], v[92:95]
	v_mfma_f32_16x16x32_f16 v[76:79], v[88:91], v[168:171], v[76:79]
	v_mfma_f32_16x16x32_f16 v[72:75], v[108:111], v[168:171], v[72:75]
	ds_read_b128 v[184:187], v245 offset:2048
	v_mfma_f32_16x16x32_f16 v[160:163], v[96:99], v[136:139], v[160:163]
	v_mfma_f32_16x16x32_f16 v[156:159], v[116:119], v[136:139], v[156:159]
	v_mfma_f32_16x16x32_f16 v[124:127], v[96:99], v[148:151], v[124:127]
	ds_read_b128 v[188:191], v245 offset:3072
	v_mfma_f32_16x16x32_f16 v[120:123], v[116:119], v[148:151], v[120:123]
	v_mfma_f32_16x16x32_f16 v[100:103], v[96:99], v[164:167], v[100:103]
	v_mfma_f32_16x16x32_f16 v[92:95], v[116:119], v[164:167], v[92:95]
	v_mfma_f32_16x16x32_f16 v[76:79], v[96:99], v[172:175], v[76:79]
	v_mfma_f32_16x16x32_f16 v[72:75], v[116:119], v[172:175], v[72:75]
	s_barrier
	s_add_i32 s65, s59, s44
	s_add_u32 s72, s26, s6
	s_addc_u32 s73, s27, s7
	s_mov_b32 m0, s65
	s_nop 0
	global_load_lds_dwordx4 v206, s[26:27]
	s_add_i32 m0, s65, 0x2000
	s_nop 0
	global_load_lds_dwordx4 v210, s[26:27]
	s_barrier
	s_waitcnt lgkmcnt(0)
	v_mfma_f32_16x16x32_f16 v[140:143], v[176:179], v[128:131], v[140:143]
	v_mfma_f32_16x16x32_f16 v[112:115], v[176:179], v[144:147], v[112:115]
	v_mfma_f32_16x16x32_f16 v[104:107], v[184:187], v[144:147], v[104:107]
	v_mfma_f32_16x16x32_f16 v[84:87], v[176:179], v[152:155], v[84:87]
	v_mfma_f32_16x16x32_f16 v[80:83], v[184:187], v[152:155], v[80:83]
	v_mfma_f32_16x16x32_f16 v[68:71], v[176:179], v[168:171], v[68:71]
	v_mfma_f32_16x16x32_f16 v[64:67], v[184:187], v[168:171], v[64:67]
	v_mfma_f32_16x16x32_f16 v[140:143], v[180:183], v[136:139], v[140:143]
	v_mfma_f32_16x16x32_f16 v[128:131], v[184:187], v[128:131], v[132:135]
	v_mfma_f32_16x16x32_f16 v[112:115], v[180:183], v[148:151], v[112:115]
	v_mfma_f32_16x16x32_f16 v[104:107], v[188:191], v[148:151], v[104:107]
	v_mfma_f32_16x16x32_f16 v[84:87], v[180:183], v[164:167], v[84:87]
	v_mfma_f32_16x16x32_f16 v[80:83], v[188:191], v[164:167], v[80:83]
	v_mfma_f32_16x16x32_f16 v[68:71], v[180:183], v[172:175], v[68:71]
	v_mfma_f32_16x16x32_f16 v[64:67], v[188:191], v[172:175], v[64:67]
	v_mfma_f32_16x16x32_f16 v[128:131], v[188:191], v[136:139], v[128:131]
	s_barrier
	s_mov_b32 m0, s23
	s_add_u32 s74, s28, s6
	s_addc_u32 s75, s29, s7
	ds_read_b128 v[132:135], v244 offset:16384
	ds_read_b128 v[136:139], v244 offset:17408
	ds_read_b128 v[144:147], v244 offset:18432
	ds_read_b128 v[148:151], v244 offset:19456
	ds_read_b128 v[152:155], v244 offset:20480
	ds_read_b128 v[164:167], v244 offset:21504
	ds_read_b128 v[168:171], v244 offset:22528
	ds_read_b128 v[172:175], v244 offset:23552
	global_load_lds_dwordx4 v204, s[28:29]
	s_mov_b32 m0, s45
	s_nop 0
	global_load_lds_dwordx4 v208, s[28:29]
	s_barrier
	s_waitcnt lgkmcnt(0)
	v_mfma_f32_16x16x32_f16 v[60:63], v[88:91], v[132:135], v[60:63]
	v_mfma_f32_16x16x32_f16 v[56:59], v[108:111], v[132:135], v[56:59]
	v_mfma_f32_16x16x32_f16 v[44:47], v[88:91], v[144:147], v[44:47]
	v_mfma_f32_16x16x32_f16 v[40:43], v[108:111], v[144:147], v[40:43]
	v_mfma_f32_16x16x32_f16 v[28:31], v[88:91], v[152:155], v[28:31]
	v_mfma_f32_16x16x32_f16 v[24:27], v[108:111], v[152:155], v[24:27]
	v_mfma_f32_16x16x32_f16 v[12:15], v[88:91], v[168:171], v[12:15]
	v_mfma_f32_16x16x32_f16 v[8:11], v[108:111], v[168:171], v[8:11]
	v_mfma_f32_16x16x32_f16 v[60:63], v[96:99], v[136:139], v[60:63]
	v_mfma_f32_16x16x32_f16 v[56:59], v[116:119], v[136:139], v[56:59]
	v_mfma_f32_16x16x32_f16 v[44:47], v[96:99], v[148:151], v[44:47]
	v_mfma_f32_16x16x32_f16 v[40:43], v[116:119], v[148:151], v[40:43]
	v_mfma_f32_16x16x32_f16 v[28:31], v[96:99], v[164:167], v[28:31]
	v_mfma_f32_16x16x32_f16 v[24:27], v[116:119], v[164:167], v[24:27]
	v_mfma_f32_16x16x32_f16 v[12:15], v[96:99], v[172:175], v[12:15]
	v_mfma_f32_16x16x32_f16 v[8:11], v[116:119], v[172:175], v[8:11]
	s_barrier
	s_add_u32 s66, s26, 0x80000
	s_addc_u32 s67, s27, 0
	s_add_i32 s65, s60, s44
	s_mov_b32 m0, s65
	s_nop 0
	global_load_lds_dwordx4 v206, s[66:67]
	s_add_i32 m0, s65, 0x2000
	s_nop 0
	global_load_lds_dwordx4 v210, s[66:67]
	s_waitcnt vmcnt(6)
	s_barrier
	v_mfma_f32_16x16x32_f16 v[52:55], v[176:179], v[132:135], v[52:55]
	v_mfma_f32_16x16x32_f16 v[48:51], v[184:187], v[132:135], v[48:51]
	v_mfma_f32_16x16x32_f16 v[36:39], v[176:179], v[144:147], v[36:39]
	v_mfma_f32_16x16x32_f16 v[32:35], v[184:187], v[144:147], v[32:35]
	v_mfma_f32_16x16x32_f16 v[20:23], v[176:179], v[152:155], v[20:23]
	v_mfma_f32_16x16x32_f16 v[16:19], v[184:187], v[152:155], v[16:19]
	v_mfma_f32_16x16x32_f16 v[4:7], v[176:179], v[168:171], v[4:7]
	v_mfma_f32_16x16x32_f16 v[0:3], v[184:187], v[168:171], v[0:3]
	v_mfma_f32_16x16x32_f16 v[52:55], v[180:183], v[136:139], v[52:55]
	v_mfma_f32_16x16x32_f16 v[48:51], v[188:191], v[136:139], v[48:51]
	v_mfma_f32_16x16x32_f16 v[36:39], v[180:183], v[148:151], v[36:39]
	v_mfma_f32_16x16x32_f16 v[32:35], v[188:191], v[148:151], v[32:35]
	v_mfma_f32_16x16x32_f16 v[20:23], v[180:183], v[164:167], v[20:23]
	v_mfma_f32_16x16x32_f16 v[16:19], v[188:191], v[164:167], v[16:19]
	v_mfma_f32_16x16x32_f16 v[4:7], v[180:183], v[172:175], v[4:7]
	v_mfma_f32_16x16x32_f16 v[0:3], v[188:191], v[172:175], v[0:3]
	s_barrier
	s_add_i32 s65, 0, 0x18000
	v_add_u32_e32 v116, s65, v241
	ds_read_b128 v[88:91], v116
	ds_read_b128 v[96:99], v116 offset:1024
	ds_read_b128 v[108:111], v116 offset:2048
	ds_read_b128 v[116:119], v116 offset:3072
	s_add_u32 s28, s28, 0x80000
	s_addc_u32 s29, s29, 0
	s_mov_b32 m0, s48
	ds_read_b128 v[132:135], v244 offset:32768
	ds_read_b128 v[136:139], v244 offset:33792
	ds_read_b128 v[144:147], v244 offset:34816
	ds_read_b128 v[148:151], v244 offset:35840
	ds_read_b128 v[152:155], v244 offset:36864
	ds_read_b128 v[164:167], v244 offset:37888
	ds_read_b128 v[168:171], v244 offset:38912
	ds_read_b128 v[172:175], v244 offset:39936
	global_load_lds_dwordx4 v204, s[28:29]
	s_mov_b32 m0, s49
	s_nop 0
	global_load_lds_dwordx4 v208, s[28:29]
	s_waitcnt lgkmcnt(8)
	s_barrier
	s_waitcnt lgkmcnt(0)
	v_mfma_f32_16x16x32_f16 v[160:163], v[88:91], v[132:135], v[160:163]
	v_mfma_f32_16x16x32_f16 v[156:159], v[108:111], v[132:135], v[156:159]
	v_add_u32_e32 v188, 0x1c000, v241
	ds_read_b128 v[176:179], v188
	v_mfma_f32_16x16x32_f16 v[124:127], v[88:91], v[144:147], v[124:127]
	v_mfma_f32_16x16x32_f16 v[120:123], v[108:111], v[144:147], v[120:123]
	v_mfma_f32_16x16x32_f16 v[100:103], v[88:91], v[152:155], v[100:103]
	ds_read_b128 v[180:183], v188 offset:1024
	v_mfma_f32_16x16x32_f16 v[92:95], v[108:111], v[152:155], v[92:95]
	v_mfma_f32_16x16x32_f16 v[76:79], v[88:91], v[168:171], v[76:79]
	v_mfma_f32_16x16x32_f16 v[72:75], v[108:111], v[168:171], v[72:75]
	ds_read_b128 v[184:187], v188 offset:2048
	v_mfma_f32_16x16x32_f16 v[160:163], v[96:99], v[136:139], v[160:163]
	v_mfma_f32_16x16x32_f16 v[156:159], v[116:119], v[136:139], v[156:159]
	v_mfma_f32_16x16x32_f16 v[124:127], v[96:99], v[148:151], v[124:127]
	ds_read_b128 v[188:191], v188 offset:3072
	v_mfma_f32_16x16x32_f16 v[120:123], v[116:119], v[148:151], v[120:123]
	v_mfma_f32_16x16x32_f16 v[100:103], v[96:99], v[164:167], v[100:103]
	v_mfma_f32_16x16x32_f16 v[92:95], v[116:119], v[164:167], v[92:95]
	v_mfma_f32_16x16x32_f16 v[76:79], v[96:99], v[172:175], v[76:79]
	v_mfma_f32_16x16x32_f16 v[72:75], v[116:119], v[172:175], v[72:75]
	s_barrier
	s_add_i32 s28, 0, 0x1c000
	s_add_i32 s29, s65, s44
	s_mov_b32 m0, s29
	s_nop 0
	global_load_lds_dwordx4 v206, s[72:73]
	s_add_i32 m0, s29, 0x2000
	s_nop 0
	global_load_lds_dwordx4 v210, s[72:73]
	s_barrier
	s_waitcnt lgkmcnt(0)
	v_mfma_f32_16x16x32_f16 v[140:143], v[176:179], v[132:135], v[140:143]
	v_mfma_f32_16x16x32_f16 v[128:131], v[184:187], v[132:135], v[128:131]
	v_mfma_f32_16x16x32_f16 v[112:115], v[176:179], v[144:147], v[112:115]
	v_mfma_f32_16x16x32_f16 v[104:107], v[184:187], v[144:147], v[104:107]
	v_mfma_f32_16x16x32_f16 v[84:87], v[176:179], v[152:155], v[84:87]
	v_mfma_f32_16x16x32_f16 v[80:83], v[184:187], v[152:155], v[80:83]
	v_mfma_f32_16x16x32_f16 v[68:71], v[176:179], v[168:171], v[68:71]
	v_mfma_f32_16x16x32_f16 v[64:67], v[184:187], v[168:171], v[64:67]
	v_mfma_f32_16x16x32_f16 v[140:143], v[180:183], v[136:139], v[140:143]
	v_mfma_f32_16x16x32_f16 v[132:135], v[188:191], v[136:139], v[128:131]
	v_mfma_f32_16x16x32_f16 v[112:115], v[180:183], v[148:151], v[112:115]
	v_mfma_f32_16x16x32_f16 v[104:107], v[188:191], v[148:151], v[104:107]
	v_mfma_f32_16x16x32_f16 v[84:87], v[180:183], v[164:167], v[84:87]
	v_mfma_f32_16x16x32_f16 v[80:83], v[188:191], v[164:167], v[80:83]
	v_mfma_f32_16x16x32_f16 v[68:71], v[180:183], v[172:175], v[68:71]
	v_mfma_f32_16x16x32_f16 v[64:67], v[188:191], v[172:175], v[64:67]
	s_barrier
	s_mov_b32 m0, s51
	ds_read_b128 v[128:131], v244 offset:49152
	ds_read_b128 v[136:139], v244 offset:50176
	ds_read_b128 v[144:147], v244 offset:51200
	ds_read_b128 v[148:151], v244 offset:52224
	ds_read_b128 v[152:155], v244 offset:53248
	ds_read_b128 v[164:167], v244 offset:54272
	ds_read_b128 v[168:171], v244 offset:55296
	ds_read_b128 v[172:175], v244 offset:56320
	global_load_lds_dwordx4 v204, s[74:75]
	s_mov_b32 m0, s54
	s_nop 0
	global_load_lds_dwordx4 v208, s[74:75]
	s_barrier
	s_waitcnt lgkmcnt(0)
	v_mfma_f32_16x16x32_f16 v[60:63], v[88:91], v[128:131], v[60:63]
	v_mfma_f32_16x16x32_f16 v[56:59], v[108:111], v[128:131], v[56:59]
	v_mfma_f32_16x16x32_f16 v[44:47], v[88:91], v[144:147], v[44:47]
	v_mfma_f32_16x16x32_f16 v[40:43], v[108:111], v[144:147], v[40:43]
	v_mfma_f32_16x16x32_f16 v[28:31], v[88:91], v[152:155], v[28:31]
	v_mfma_f32_16x16x32_f16 v[24:27], v[108:111], v[152:155], v[24:27]
	v_mfma_f32_16x16x32_f16 v[12:15], v[88:91], v[168:171], v[12:15]
	v_mfma_f32_16x16x32_f16 v[8:11], v[108:111], v[168:171], v[8:11]
	v_mfma_f32_16x16x32_f16 v[60:63], v[96:99], v[136:139], v[60:63]
	v_mfma_f32_16x16x32_f16 v[56:59], v[116:119], v[136:139], v[56:59]
	v_mfma_f32_16x16x32_f16 v[44:47], v[96:99], v[148:151], v[44:47]
	v_mfma_f32_16x16x32_f16 v[40:43], v[116:119], v[148:151], v[40:43]
	v_mfma_f32_16x16x32_f16 v[28:31], v[96:99], v[164:167], v[28:31]
	v_mfma_f32_16x16x32_f16 v[24:27], v[116:119], v[164:167], v[24:27]
	v_mfma_f32_16x16x32_f16 v[12:15], v[96:99], v[172:175], v[12:15]
	v_mfma_f32_16x16x32_f16 v[8:11], v[116:119], v[172:175], v[8:11]
	s_barrier
	s_add_u32 s26, s26, 0x80080
	s_addc_u32 s27, s27, 0
	s_add_i32 s28, s28, s44
	s_mov_b32 m0, s28
	s_nop 0
	global_load_lds_dwordx4 v206, s[26:27]
	s_add_i32 m0, s28, 0x2000
	s_nop 0
	global_load_lds_dwordx4 v210, s[26:27]
	s_waitcnt vmcnt(6)
	s_barrier
	v_mfma_f32_16x16x32_f16 v[52:55], v[176:179], v[128:131], v[52:55]
	v_mfma_f32_16x16x32_f16 v[48:51], v[184:187], v[128:131], v[48:51]
	v_mfma_f32_16x16x32_f16 v[36:39], v[176:179], v[144:147], v[36:39]
	v_mfma_f32_16x16x32_f16 v[32:35], v[184:187], v[144:147], v[32:35]
	v_mfma_f32_16x16x32_f16 v[20:23], v[176:179], v[152:155], v[20:23]
	v_mfma_f32_16x16x32_f16 v[16:19], v[184:187], v[152:155], v[16:19]
	v_mfma_f32_16x16x32_f16 v[4:7], v[176:179], v[168:171], v[4:7]
	v_mfma_f32_16x16x32_f16 v[0:3], v[184:187], v[168:171], v[0:3]
	v_mfma_f32_16x16x32_f16 v[52:55], v[180:183], v[136:139], v[52:55]
	v_mfma_f32_16x16x32_f16 v[48:51], v[188:191], v[136:139], v[48:51]
	v_mfma_f32_16x16x32_f16 v[36:39], v[180:183], v[148:151], v[36:39]
	v_mfma_f32_16x16x32_f16 v[32:35], v[188:191], v[148:151], v[32:35]
	v_mfma_f32_16x16x32_f16 v[20:23], v[180:183], v[164:167], v[20:23]
	v_mfma_f32_16x16x32_f16 v[16:19], v[188:191], v[164:167], v[16:19]
	v_mfma_f32_16x16x32_f16 v[4:7], v[180:183], v[172:175], v[4:7]
	v_mfma_f32_16x16x32_f16 v[0:3], v[188:191], v[172:175], v[0:3]
	s_barrier
	s_add_i32 s64, s64, 2
	s_add_u32 s24, s24, 0x100
	s_addc_u32 s25, s25, 0
	s_add_u32 s62, s62, 0x100
	s_addc_u32 s63, s63, 0
	s_cmp_gt_u32 s64, 29
	s_cbranch_scc0 .LBB0_1185
	s_setprio 0
	s_lshl_b32 s15, s22, 8
	s_add_i32 s17, s15, 0xffffe000
	s_lshr_b32 s17, s17, 11
	s_mulk_i32 s17, 0x1800
	s_addk_i32 s17, 0x1800
	s_cmp_gt_i32 s22, 31
	s_cselect_b32 s24, s17, 0
	s_ashr_i32 s25, s24, 31
	v_lshl_or_b32 v128, s30, 8, v242
	s_lshl_b64 s[24:25], s[24:25], 2
	s_add_u32 s24, s42, s24
	v_ashrrev_i32_e32 v129, 31, v128
	v_add_u32_e32 v130, s15, v240
	s_addc_u32 s25, s43, s25
	v_lshlrev_b64 v[220:221], 1, v[128:129]
	v_ashrrev_i32_e32 v131, 31, v130
	v_lshl_add_u64 v[96:97], v[128:129], 2, s[24:25]
	v_lshl_add_u64 v[128:129], s[4:5], 0, v[220:221]
	v_lshlrev_b64 v[236:237], 12, v[130:131]
	v_lshl_add_u64 v[136:137], v[128:129], 0, v[236:237]
	global_load_dwordx4 v[108:111], v[96:97], off offset:16
	global_load_dwordx4 v[116:119], v[96:97], off
	global_load_dwordx4 v[88:91], v[96:97], off offset:528
	s_nop 0
	global_load_dwordx4 v[96:99], v[96:97], off offset:512
	s_nop 0
	global_load_dwordx4 v[246:249], v[136:137], off nt
	global_load_dwordx4 v[200:203], v[136:137], off offset:256 nt
	v_or_b32_e32 v136, 16, v130
	v_ashrrev_i32_e32 v137, 31, v136
	v_lshlrev_b64 v[234:235], 12, v[136:137]
	v_lshl_add_u64 v[136:137], v[128:129], 0, v[234:235]
	global_load_dwordx4 v[196:199], v[136:137], off nt
	global_load_dwordx4 v[192:195], v[136:137], off offset:256 nt
	v_or_b32_e32 v136, 32, v130
	v_ashrrev_i32_e32 v137, 31, v136
	v_lshlrev_b64 v[232:233], 12, v[136:137]
	v_lshl_add_u64 v[136:137], v[128:129], 0, v[232:233]
	global_load_dwordx4 v[188:191], v[136:137], off nt
	global_load_dwordx4 v[184:187], v[136:137], off offset:256 nt
	v_readlane_b32 s64, v254, 21
	v_readlane_b32 s68, v254, 25
	v_readlane_b32 s69, v254, 26
	s_mov_b64 s[56:57], s[68:69]
	v_or_b32_e32 v130, 48, v130
	v_ashrrev_i32_e32 v131, 31, v130
	v_lshlrev_b64 v[230:231], 12, v[130:131]
	v_lshl_add_u64 v[130:131], v[128:129], 0, v[230:231]
	global_load_dwordx4 v[180:183], v[130:131], off nt
	global_load_dwordx4 v[176:179], v[130:131], off offset:256 nt
	v_lshl_add_u64 v[228:229], v[236:237], 0, s[0:1]
	v_lshl_add_u64 v[130:131], v[128:129], 0, v[228:229]
	global_load_dwordx4 v[172:175], v[130:131], off nt
	global_load_dwordx4 v[168:171], v[130:131], off offset:256 nt
	v_lshl_add_u64 v[226:227], v[236:237], 0, s[8:9]
	v_lshl_add_u64 v[130:131], v[128:129], 0, v[226:227]
	global_load_dwordx4 v[164:167], v[130:131], off nt
	global_load_dwordx4 v[152:155], v[130:131], off offset:256 nt
	v_lshl_add_u64 v[224:225], v[236:237], 0, s[10:11]
	v_lshl_add_u64 v[130:131], v[128:129], 0, v[224:225]
	global_load_dwordx4 v[148:151], v[130:131], off nt
	global_load_dwordx4 v[144:147], v[130:131], off offset:256 nt
	v_lshl_add_u64 v[222:223], v[236:237], 0, s[12:13]
	v_lshl_add_u64 v[128:129], v[128:129], 0, v[222:223]
	global_load_dwordx4 v[136:139], v[128:129], off nt
	s_nop 0
	global_load_dwordx4 v[128:131], v[128:129], off offset:256 nt
	s_and_b64 vcc, exec, s[2:3]
	s_mov_b32 s30, s14
	s_mov_b32 s22, s16
	s_mov_b64 s[26:27], s[20:21]
	s_mov_b64 s[24:25], s[18:19]
	v_readlane_b32 s65, v254, 22
	v_readlane_b32 s66, v254, 23
	v_readlane_b32 s67, v254, 24
	v_readlane_b32 s70, v254, 27
	v_readlane_b32 s71, v254, 28
	v_readlane_b32 s72, v254, 29
	v_readlane_b32 s73, v254, 30
	v_readlane_b32 s74, v254, 31
	v_readlane_b32 s75, v254, 32
	v_readlane_b32 s76, v254, 33
	v_readlane_b32 s77, v254, 34
	v_readlane_b32 s78, v254, 35
	v_readlane_b32 s79, v254, 36
	s_waitcnt vmcnt(0)
	v_cvt_f32_f16_e32 v250, v246
	v_cvt_f32_f16_sdwa v251, v246 dst_sel:DWORD dst_unused:UNUSED_PAD src0_sel:WORD_1
	v_pk_fma_f32 v[160:161], v[160:161], v[116:117], v[250:251]
	s_nop 0
	v_cvt_pk_f16_f32 v246, v160, v161
	v_cvt_f32_f16_e32 v160, v248
	v_cvt_f32_f16_sdwa v161, v248 dst_sel:DWORD dst_unused:UNUSED_PAD src0_sel:WORD_1
	v_pk_fma_f32 v[156:157], v[156:157], v[108:109], v[160:161]
	s_nop 0
	v_cvt_pk_f16_f32 v248, v156, v157
	v_cvt_f32_f16_e32 v156, v247
	v_cvt_f32_f16_sdwa v157, v247 dst_sel:DWORD dst_unused:UNUSED_PAD src0_sel:WORD_1
	v_pk_fma_f32 v[156:157], v[162:163], v[118:119], v[156:157]
	s_nop 0
	v_cvt_pk_f16_f32 v247, v156, v157
	v_cvt_f32_f16_e32 v156, v249
	v_cvt_f32_f16_sdwa v157, v249 dst_sel:DWORD dst_unused:UNUSED_PAD src0_sel:WORD_1
	v_pk_fma_f32 v[156:157], v[158:159], v[110:111], v[156:157]
	s_nop 0
	v_cvt_pk_f16_f32 v249, v156, v157
	v_lshl_add_u64 v[156:157], s[56:57], 0, v[236:237]
	v_lshl_add_u64 v[160:161], v[156:157], 0, v[220:221]
	v_cvt_f32_f16_e32 v156, v200
	v_cvt_f32_f16_sdwa v157, v200 dst_sel:DWORD dst_unused:UNUSED_PAD src0_sel:WORD_1
	global_store_dwordx4 v[160:161], v[246:249], off
	v_pk_fma_f32 v[140:141], v[140:141], v[96:97], v[156:157]
	s_nop 0
	v_cvt_pk_f16_f32 v156, v140, v141
	v_cvt_f32_f16_e32 v140, v202
	v_cvt_f32_f16_sdwa v141, v202 dst_sel:DWORD dst_unused:UNUSED_PAD src0_sel:WORD_1
	v_pk_fma_f32 v[132:133], v[132:133], v[88:89], v[140:141]
	s_nop 0
	v_cvt_pk_f16_f32 v158, v132, v133
	v_cvt_f32_f16_e32 v132, v201
	v_cvt_f32_f16_sdwa v133, v201 dst_sel:DWORD dst_unused:UNUSED_PAD src0_sel:WORD_1
	v_pk_fma_f32 v[132:133], v[142:143], v[98:99], v[132:133]
	s_nop 0
	v_cvt_pk_f16_f32 v157, v132, v133
	v_cvt_f32_f16_e32 v132, v203
	v_cvt_f32_f16_sdwa v133, v203 dst_sel:DWORD dst_unused:UNUSED_PAD src0_sel:WORD_1
	v_pk_fma_f32 v[132:133], v[134:135], v[90:91], v[132:133]
	s_nop 0
	v_cvt_pk_f16_f32 v159, v132, v133
	v_cvt_f32_f16_e32 v132, v196
	v_cvt_f32_f16_sdwa v133, v196 dst_sel:DWORD dst_unused:UNUSED_PAD src0_sel:WORD_1
	global_store_dwordx4 v[160:161], v[156:159], off offset:256
	v_pk_fma_f32 v[124:125], v[124:125], v[116:117], v[132:133]
	s_nop 0
	v_cvt_pk_f16_f32 v132, v124, v125
	v_cvt_f32_f16_e32 v124, v198
	v_cvt_f32_f16_sdwa v125, v198 dst_sel:DWORD dst_unused:UNUSED_PAD src0_sel:WORD_1
	v_pk_fma_f32 v[120:121], v[120:121], v[108:109], v[124:125]
	s_nop 0
	v_cvt_pk_f16_f32 v134, v120, v121
	v_cvt_f32_f16_e32 v120, v197
	v_cvt_f32_f16_sdwa v121, v197 dst_sel:DWORD dst_unused:UNUSED_PAD src0_sel:WORD_1
	v_pk_fma_f32 v[120:121], v[126:127], v[118:119], v[120:121]
	s_nop 0
	v_cvt_pk_f16_f32 v133, v120, v121
	v_cvt_f32_f16_e32 v120, v199
	v_cvt_f32_f16_sdwa v121, v199 dst_sel:DWORD dst_unused:UNUSED_PAD src0_sel:WORD_1
	v_pk_fma_f32 v[120:121], v[122:123], v[110:111], v[120:121]
	s_nop 0
	v_cvt_pk_f16_f32 v135, v120, v121
	v_lshl_add_u64 v[120:121], s[56:57], 0, v[234:235]
	v_lshl_add_u64 v[124:125], v[120:121], 0, v[220:221]
	v_cvt_f32_f16_e32 v120, v192
	v_cvt_f32_f16_sdwa v121, v192 dst_sel:DWORD dst_unused:UNUSED_PAD src0_sel:WORD_1
	global_store_dwordx4 v[124:125], v[132:135], off
	v_pk_fma_f32 v[112:113], v[112:113], v[96:97], v[120:121]
	s_nop 0
	v_cvt_pk_f16_f32 v120, v112, v113
	v_cvt_f32_f16_e32 v112, v194
	v_cvt_f32_f16_sdwa v113, v194 dst_sel:DWORD dst_unused:UNUSED_PAD src0_sel:WORD_1
	v_pk_fma_f32 v[104:105], v[104:105], v[88:89], v[112:113]
	s_nop 0
	v_cvt_pk_f16_f32 v122, v104, v105
	v_cvt_f32_f16_e32 v104, v193
	v_cvt_f32_f16_sdwa v105, v193 dst_sel:DWORD dst_unused:UNUSED_PAD src0_sel:WORD_1
	v_pk_fma_f32 v[104:105], v[114:115], v[98:99], v[104:105]
	s_nop 0
	v_cvt_pk_f16_f32 v121, v104, v105
	v_cvt_f32_f16_e32 v104, v195
	v_cvt_f32_f16_sdwa v105, v195 dst_sel:DWORD dst_unused:UNUSED_PAD src0_sel:WORD_1
	v_pk_fma_f32 v[104:105], v[106:107], v[90:91], v[104:105]
	s_nop 0
	v_cvt_pk_f16_f32 v123, v104, v105
	v_cvt_f32_f16_e32 v104, v188
	v_cvt_f32_f16_sdwa v105, v188 dst_sel:DWORD dst_unused:UNUSED_PAD src0_sel:WORD_1
	global_store_dwordx4 v[124:125], v[120:123], off offset:256
	v_pk_fma_f32 v[100:101], v[100:101], v[116:117], v[104:105]
	s_nop 0
	v_cvt_pk_f16_f32 v104, v100, v101
	v_cvt_f32_f16_e32 v100, v190
	v_cvt_f32_f16_sdwa v101, v190 dst_sel:DWORD dst_unused:UNUSED_PAD src0_sel:WORD_1
	v_pk_fma_f32 v[92:93], v[92:93], v[108:109], v[100:101]
	s_nop 0
	v_cvt_pk_f16_f32 v106, v92, v93
	v_cvt_f32_f16_e32 v92, v189
	v_cvt_f32_f16_sdwa v93, v189 dst_sel:DWORD dst_unused:UNUSED_PAD src0_sel:WORD_1
	v_pk_fma_f32 v[92:93], v[102:103], v[118:119], v[92:93]
	s_nop 0
	v_cvt_pk_f16_f32 v105, v92, v93
	v_cvt_f32_f16_e32 v92, v191
	v_cvt_f32_f16_sdwa v93, v191 dst_sel:DWORD dst_unused:UNUSED_PAD src0_sel:WORD_1
	v_pk_fma_f32 v[92:93], v[94:95], v[110:111], v[92:93]
	s_nop 0
	v_cvt_pk_f16_f32 v107, v92, v93
	v_lshl_add_u64 v[92:93], s[56:57], 0, v[232:233]
	v_lshl_add_u64 v[100:101], v[92:93], 0, v[220:221]
	v_cvt_f32_f16_e32 v92, v184
	v_cvt_f32_f16_sdwa v93, v184 dst_sel:DWORD dst_unused:UNUSED_PAD src0_sel:WORD_1
	global_store_dwordx4 v[100:101], v[104:107], off
	v_pk_fma_f32 v[84:85], v[84:85], v[96:97], v[92:93]
	s_nop 0
	v_cvt_pk_f16_f32 v92, v84, v85
	v_cvt_f32_f16_e32 v84, v186
	v_cvt_f32_f16_sdwa v85, v186 dst_sel:DWORD dst_unused:UNUSED_PAD src0_sel:WORD_1
	v_pk_fma_f32 v[80:81], v[80:81], v[88:89], v[84:85]
	s_nop 0
	v_cvt_pk_f16_f32 v94, v80, v81
	v_cvt_f32_f16_e32 v80, v185
	v_cvt_f32_f16_sdwa v81, v185 dst_sel:DWORD dst_unused:UNUSED_PAD src0_sel:WORD_1
	v_pk_fma_f32 v[80:81], v[86:87], v[98:99], v[80:81]
	s_nop 0
	v_cvt_pk_f16_f32 v93, v80, v81
	v_cvt_f32_f16_e32 v80, v187
	v_cvt_f32_f16_sdwa v81, v187 dst_sel:DWORD dst_unused:UNUSED_PAD src0_sel:WORD_1
	v_pk_fma_f32 v[80:81], v[82:83], v[90:91], v[80:81]
	s_nop 0
	v_cvt_pk_f16_f32 v95, v80, v81
	v_cvt_f32_f16_e32 v80, v180
	v_cvt_f32_f16_sdwa v81, v180 dst_sel:DWORD dst_unused:UNUSED_PAD src0_sel:WORD_1
	global_store_dwordx4 v[100:101], v[92:95], off offset:256
	v_pk_fma_f32 v[76:77], v[76:77], v[116:117], v[80:81]
	s_nop 0
	v_cvt_pk_f16_f32 v80, v76, v77
	v_cvt_f32_f16_e32 v76, v182
	v_cvt_f32_f16_sdwa v77, v182 dst_sel:DWORD dst_unused:UNUSED_PAD src0_sel:WORD_1
	v_pk_fma_f32 v[72:73], v[72:73], v[108:109], v[76:77]
	s_nop 0
	v_cvt_pk_f16_f32 v82, v72, v73
	v_cvt_f32_f16_e32 v72, v181
	v_cvt_f32_f16_sdwa v73, v181 dst_sel:DWORD dst_unused:UNUSED_PAD src0_sel:WORD_1
	v_pk_fma_f32 v[72:73], v[78:79], v[118:119], v[72:73]
	s_nop 0
	v_cvt_pk_f16_f32 v81, v72, v73
	v_cvt_f32_f16_e32 v72, v183
	v_cvt_f32_f16_sdwa v73, v183 dst_sel:DWORD dst_unused:UNUSED_PAD src0_sel:WORD_1
	v_pk_fma_f32 v[72:73], v[74:75], v[110:111], v[72:73]
	s_nop 0
	v_cvt_pk_f16_f32 v83, v72, v73
	v_lshl_add_u64 v[72:73], s[56:57], 0, v[230:231]
	v_lshl_add_u64 v[76:77], v[72:73], 0, v[220:221]
	v_cvt_f32_f16_e32 v72, v176
	v_cvt_f32_f16_sdwa v73, v176 dst_sel:DWORD dst_unused:UNUSED_PAD src0_sel:WORD_1
	global_store_dwordx4 v[76:77], v[80:83], off
	v_pk_fma_f32 v[68:69], v[68:69], v[96:97], v[72:73]
	s_nop 0
	v_cvt_pk_f16_f32 v72, v68, v69
	v_cvt_f32_f16_e32 v68, v178
	v_cvt_f32_f16_sdwa v69, v178 dst_sel:DWORD dst_unused:UNUSED_PAD src0_sel:WORD_1
	v_pk_fma_f32 v[64:65], v[64:65], v[88:89], v[68:69]
	s_nop 0
	v_cvt_pk_f16_f32 v74, v64, v65
	v_cvt_f32_f16_e32 v64, v177
	v_cvt_f32_f16_sdwa v65, v177 dst_sel:DWORD dst_unused:UNUSED_PAD src0_sel:WORD_1
	v_pk_fma_f32 v[64:65], v[70:71], v[98:99], v[64:65]
	s_nop 0
	v_cvt_pk_f16_f32 v73, v64, v65
	v_cvt_f32_f16_e32 v64, v179
	v_cvt_f32_f16_sdwa v65, v179 dst_sel:DWORD dst_unused:UNUSED_PAD src0_sel:WORD_1
	v_pk_fma_f32 v[64:65], v[66:67], v[90:91], v[64:65]
	s_nop 0
	v_cvt_pk_f16_f32 v75, v64, v65
	v_cvt_f32_f16_e32 v64, v172
	v_cvt_f32_f16_sdwa v65, v172 dst_sel:DWORD dst_unused:UNUSED_PAD src0_sel:WORD_1
	global_store_dwordx4 v[76:77], v[72:75], off offset:256
	v_pk_fma_f32 v[60:61], v[60:61], v[116:117], v[64:65]
	s_nop 0
	v_cvt_pk_f16_f32 v64, v60, v61
	v_cvt_f32_f16_e32 v60, v174
	v_cvt_f32_f16_sdwa v61, v174 dst_sel:DWORD dst_unused:UNUSED_PAD src0_sel:WORD_1
	v_pk_fma_f32 v[56:57], v[56:57], v[108:109], v[60:61]
	s_nop 0
	v_cvt_pk_f16_f32 v66, v56, v57
	v_cvt_f32_f16_e32 v56, v173
	v_cvt_f32_f16_sdwa v57, v173 dst_sel:DWORD dst_unused:UNUSED_PAD src0_sel:WORD_1
	v_pk_fma_f32 v[56:57], v[62:63], v[118:119], v[56:57]
	s_nop 0
	v_cvt_pk_f16_f32 v65, v56, v57
	v_cvt_f32_f16_e32 v56, v175
	v_cvt_f32_f16_sdwa v57, v175 dst_sel:DWORD dst_unused:UNUSED_PAD src0_sel:WORD_1
	v_pk_fma_f32 v[56:57], v[58:59], v[110:111], v[56:57]
	s_nop 0
	v_cvt_pk_f16_f32 v67, v56, v57
	v_lshl_add_u64 v[56:57], s[56:57], 0, v[228:229]
	v_lshl_add_u64 v[60:61], v[56:57], 0, v[220:221]
	v_cvt_f32_f16_e32 v56, v168
	v_cvt_f32_f16_sdwa v57, v168 dst_sel:DWORD dst_unused:UNUSED_PAD src0_sel:WORD_1
	global_store_dwordx4 v[60:61], v[64:67], off
	v_pk_fma_f32 v[52:53], v[52:53], v[96:97], v[56:57]
	s_nop 0
	v_cvt_pk_f16_f32 v56, v52, v53
	v_cvt_f32_f16_e32 v52, v170
	v_cvt_f32_f16_sdwa v53, v170 dst_sel:DWORD dst_unused:UNUSED_PAD src0_sel:WORD_1
	v_pk_fma_f32 v[48:49], v[48:49], v[88:89], v[52:53]
	s_nop 0
	v_cvt_pk_f16_f32 v58, v48, v49
	v_cvt_f32_f16_e32 v48, v169
	v_cvt_f32_f16_sdwa v49, v169 dst_sel:DWORD dst_unused:UNUSED_PAD src0_sel:WORD_1
	v_pk_fma_f32 v[48:49], v[54:55], v[98:99], v[48:49]
	s_nop 0
	v_cvt_pk_f16_f32 v57, v48, v49
	v_cvt_f32_f16_e32 v48, v171
	v_cvt_f32_f16_sdwa v49, v171 dst_sel:DWORD dst_unused:UNUSED_PAD src0_sel:WORD_1
	v_pk_fma_f32 v[48:49], v[50:51], v[90:91], v[48:49]
	s_nop 0
	v_cvt_pk_f16_f32 v59, v48, v49
	v_cvt_f32_f16_e32 v48, v164
	v_cvt_f32_f16_sdwa v49, v164 dst_sel:DWORD dst_unused:UNUSED_PAD src0_sel:WORD_1
	global_store_dwordx4 v[60:61], v[56:59], off offset:256
	v_pk_fma_f32 v[44:45], v[44:45], v[116:117], v[48:49]
	s_nop 0
	v_cvt_pk_f16_f32 v48, v44, v45
	v_cvt_f32_f16_e32 v44, v166
	v_cvt_f32_f16_sdwa v45, v166 dst_sel:DWORD dst_unused:UNUSED_PAD src0_sel:WORD_1
	v_pk_fma_f32 v[40:41], v[40:41], v[108:109], v[44:45]
	s_nop 0
	v_cvt_pk_f16_f32 v50, v40, v41
	v_cvt_f32_f16_e32 v40, v165
	v_cvt_f32_f16_sdwa v41, v165 dst_sel:DWORD dst_unused:UNUSED_PAD src0_sel:WORD_1
	v_pk_fma_f32 v[40:41], v[46:47], v[118:119], v[40:41]
	s_nop 0
	v_cvt_pk_f16_f32 v49, v40, v41
	v_cvt_f32_f16_e32 v40, v167
	v_cvt_f32_f16_sdwa v41, v167 dst_sel:DWORD dst_unused:UNUSED_PAD src0_sel:WORD_1
	v_pk_fma_f32 v[40:41], v[42:43], v[110:111], v[40:41]
	s_nop 0
	v_cvt_pk_f16_f32 v51, v40, v41
	v_lshl_add_u64 v[40:41], s[56:57], 0, v[226:227]
	v_lshl_add_u64 v[44:45], v[40:41], 0, v[220:221]
	v_cvt_f32_f16_e32 v40, v152
	v_cvt_f32_f16_sdwa v41, v152 dst_sel:DWORD dst_unused:UNUSED_PAD src0_sel:WORD_1
	global_store_dwordx4 v[44:45], v[48:51], off
	v_pk_fma_f32 v[36:37], v[36:37], v[96:97], v[40:41]
	s_nop 0
	v_cvt_pk_f16_f32 v40, v36, v37
	v_cvt_f32_f16_e32 v36, v154
	v_cvt_f32_f16_sdwa v37, v154 dst_sel:DWORD dst_unused:UNUSED_PAD src0_sel:WORD_1
	v_pk_fma_f32 v[32:33], v[32:33], v[88:89], v[36:37]
	s_nop 0
	v_cvt_pk_f16_f32 v42, v32, v33
	v_cvt_f32_f16_e32 v32, v153
	v_cvt_f32_f16_sdwa v33, v153 dst_sel:DWORD dst_unused:UNUSED_PAD src0_sel:WORD_1
	v_pk_fma_f32 v[32:33], v[38:39], v[98:99], v[32:33]
	s_nop 0
	v_cvt_pk_f16_f32 v41, v32, v33
	v_cvt_f32_f16_e32 v32, v155
	v_cvt_f32_f16_sdwa v33, v155 dst_sel:DWORD dst_unused:UNUSED_PAD src0_sel:WORD_1
	v_pk_fma_f32 v[32:33], v[34:35], v[90:91], v[32:33]
	s_nop 0
	v_cvt_pk_f16_f32 v43, v32, v33
	v_cvt_f32_f16_e32 v32, v148
	v_cvt_f32_f16_sdwa v33, v148 dst_sel:DWORD dst_unused:UNUSED_PAD src0_sel:WORD_1
	global_store_dwordx4 v[44:45], v[40:43], off offset:256
	v_pk_fma_f32 v[28:29], v[28:29], v[116:117], v[32:33]
	s_nop 0
	v_cvt_pk_f16_f32 v32, v28, v29
	v_cvt_f32_f16_e32 v28, v150
	v_cvt_f32_f16_sdwa v29, v150 dst_sel:DWORD dst_unused:UNUSED_PAD src0_sel:WORD_1
	v_pk_fma_f32 v[24:25], v[24:25], v[108:109], v[28:29]
	s_nop 0
	v_cvt_pk_f16_f32 v34, v24, v25
	v_cvt_f32_f16_e32 v24, v149
	v_cvt_f32_f16_sdwa v25, v149 dst_sel:DWORD dst_unused:UNUSED_PAD src0_sel:WORD_1
	v_pk_fma_f32 v[24:25], v[30:31], v[118:119], v[24:25]
	s_nop 0
	v_cvt_pk_f16_f32 v33, v24, v25
	v_cvt_f32_f16_e32 v24, v151
	v_cvt_f32_f16_sdwa v25, v151 dst_sel:DWORD dst_unused:UNUSED_PAD src0_sel:WORD_1
	v_pk_fma_f32 v[24:25], v[26:27], v[110:111], v[24:25]
	s_nop 0
	v_cvt_pk_f16_f32 v35, v24, v25
	v_lshl_add_u64 v[24:25], s[56:57], 0, v[224:225]
	v_lshl_add_u64 v[28:29], v[24:25], 0, v[220:221]
	v_cvt_f32_f16_e32 v24, v144
	v_cvt_f32_f16_sdwa v25, v144 dst_sel:DWORD dst_unused:UNUSED_PAD src0_sel:WORD_1
	global_store_dwordx4 v[28:29], v[32:35], off
	v_pk_fma_f32 v[20:21], v[20:21], v[96:97], v[24:25]
	s_nop 0
	v_cvt_pk_f16_f32 v24, v20, v21
	v_cvt_f32_f16_e32 v20, v146
	v_cvt_f32_f16_sdwa v21, v146 dst_sel:DWORD dst_unused:UNUSED_PAD src0_sel:WORD_1
	v_pk_fma_f32 v[16:17], v[16:17], v[88:89], v[20:21]
	s_nop 0
	v_cvt_pk_f16_f32 v26, v16, v17
	v_cvt_f32_f16_e32 v16, v145
	v_cvt_f32_f16_sdwa v17, v145 dst_sel:DWORD dst_unused:UNUSED_PAD src0_sel:WORD_1
	v_pk_fma_f32 v[16:17], v[22:23], v[98:99], v[16:17]
	s_nop 0
	v_cvt_pk_f16_f32 v25, v16, v17
	v_cvt_f32_f16_e32 v16, v147
	v_cvt_f32_f16_sdwa v17, v147 dst_sel:DWORD dst_unused:UNUSED_PAD src0_sel:WORD_1
	v_pk_fma_f32 v[16:17], v[18:19], v[90:91], v[16:17]
	s_nop 0
	v_cvt_pk_f16_f32 v27, v16, v17
	v_cvt_f32_f16_e32 v16, v136
	v_cvt_f32_f16_sdwa v17, v136 dst_sel:DWORD dst_unused:UNUSED_PAD src0_sel:WORD_1
	global_store_dwordx4 v[28:29], v[24:27], off offset:256
	v_pk_fma_f32 v[12:13], v[12:13], v[116:117], v[16:17]
	s_nop 0
	v_cvt_pk_f16_f32 v16, v12, v13
	v_cvt_f32_f16_e32 v12, v138
	v_cvt_f32_f16_sdwa v13, v138 dst_sel:DWORD dst_unused:UNUSED_PAD src0_sel:WORD_1
	v_pk_fma_f32 v[8:9], v[8:9], v[108:109], v[12:13]
	s_nop 0
	v_cvt_pk_f16_f32 v18, v8, v9
	v_cvt_f32_f16_e32 v8, v137
	v_cvt_f32_f16_sdwa v9, v137 dst_sel:DWORD dst_unused:UNUSED_PAD src0_sel:WORD_1
	v_pk_fma_f32 v[8:9], v[14:15], v[118:119], v[8:9]
	s_nop 0
	v_cvt_pk_f16_f32 v17, v8, v9
	v_cvt_f32_f16_e32 v8, v139
	v_cvt_f32_f16_sdwa v9, v139 dst_sel:DWORD dst_unused:UNUSED_PAD src0_sel:WORD_1
	v_pk_fma_f32 v[8:9], v[10:11], v[110:111], v[8:9]
	s_nop 0
	v_cvt_pk_f16_f32 v19, v8, v9
	v_lshl_add_u64 v[8:9], s[56:57], 0, v[222:223]
	v_lshl_add_u64 v[12:13], v[8:9], 0, v[220:221]
	v_cvt_f32_f16_e32 v8, v128
	v_cvt_f32_f16_sdwa v9, v128 dst_sel:DWORD dst_unused:UNUSED_PAD src0_sel:WORD_1
	global_store_dwordx4 v[12:13], v[16:19], off
	v_pk_fma_f32 v[4:5], v[4:5], v[96:97], v[8:9]
	s_nop 0
	v_cvt_pk_f16_f32 v8, v4, v5
	v_cvt_f32_f16_e32 v4, v130
	v_cvt_f32_f16_sdwa v5, v130 dst_sel:DWORD dst_unused:UNUSED_PAD src0_sel:WORD_1
	v_pk_fma_f32 v[0:1], v[0:1], v[88:89], v[4:5]
	s_nop 0
	v_cvt_pk_f16_f32 v10, v0, v1
	v_cvt_f32_f16_e32 v0, v129
	v_cvt_f32_f16_sdwa v1, v129 dst_sel:DWORD dst_unused:UNUSED_PAD src0_sel:WORD_1
	v_pk_fma_f32 v[0:1], v[6:7], v[98:99], v[0:1]
	s_nop 0
	v_cvt_pk_f16_f32 v9, v0, v1
	v_cvt_f32_f16_e32 v0, v131
	v_cvt_f32_f16_sdwa v1, v131 dst_sel:DWORD dst_unused:UNUSED_PAD src0_sel:WORD_1
	v_pk_fma_f32 v[0:1], v[2:3], v[90:91], v[0:1]
	s_nop 0
	v_cvt_pk_f16_f32 v11, v0, v1
	global_store_dwordx4 v[12:13], v[8:11], off offset:256
	s_cbranch_vccz .LBB0_1178
	s_waitcnt vmcnt(0)
	s_cmpk_gt_u32 s34, 0xff
	s_cbranch_scc1 .LBB0_1189
	s_barrier
